# v81 + GEMM K-loops: loop bookkeeping hopped in front of the loop-back barrier (sec 7.11); up/down GEMM loop-invariant LDS fragment addresses hoisted out of the loop (VALU-free load phases)
# speedup vs baseline: 1.0022x; 1.0022x over previous
; #define PG8_STAGE(bufoff, gbase, voff) do { _Pragma("unroll") for (int _i = 0; _i < 2; ++_i) \
;         __builtin_amdgcn_global_load_lds((const unsigned*)((const char*)(gbase) + (voff)[_i]), (PG8_LAS unsigned*)(lds + (bufoff) + ldsw + _i * 8192), 16, 0, 0); } while (0)
; #define PG8_LDA(dst, b, h) do { _Pragma("unroll") for (int m = 0; m < 4; ++m) _Pragma("unroll") for (int k = 0; k < 2; ++k) dst[m][k] = *(const PG8_LAS bf16x8*)(lds + PG8_SA(b, h) + aoff + m * 2048 + k * 1024); } while (0)
; #define PG8_LDB(dst, b, h) do { _Pragma("unroll") for (int n = 0; n < 2; ++n) _Pragma("unroll") for (int k = 0; k < 2; ++k) dst[n][k] = *(const PG8_LAS bf16x8*)(lds + PG8_SB(b, h) + boff + n * 2048 + k * 1024); } while (0)
; #define PG8_MMA(ai, bj, At, Bt) do { __builtin_amdgcn_s_setprio(1); _Pragma("unroll") for (int m = 0; m < 4; ++m) _Pragma("unroll") for (int n = 0; n < 2; ++n) _Pragma("unroll") for (int k = 0; k < 2; ++k) \
;         acc[ai][bj][m][n] = __builtin_amdgcn_mfma_f32_16x16x32_bf16(Bt[n][k], At[m][k], acc[ai][bj][m][n], 0, 0, 0); __builtin_amdgcn_s_setprio(0); } while (0)
; #define PG8_WAIT_V(n) asm volatile("s_waitcnt vmcnt(" #n ")" ::: "memory")
; #define PG8_BAR __builtin_amdgcn_s_barrier()
; template <class Epi, class Sched, bool ALIGN_EPI = false, bool SP2 = false>
; __device__ __forceinline__ void gemm_phase(PG8_LAS unsigned char* lds, const Gemm g, const Sched& S, const Epi& E, int wv) {
;     ...
;         for (int t = 0; t < nt; t += 2) {
;             const bool last = (t == nt - 2);
;             const char* a1 = cA + (size_t)(t + 1) * kstep;
;             const char* a2 = last ? nA : cA + (size_t)(t + 2) * kstep; const char* b2 = last ? nB : cB + (size_t)(t + 2) * kstep;
;             const char* a3 = a2 + kstep; const char* b3 = b2 + kstep;
;             if (last && has_next) S.a_ready(nxt);
;             if constexpr (SP2) {
;             PG8_LDB(B0, 0, 0); PG8_LDB(B1, 0, 1); PG8_SCHED; PG8_LDA(At, 0, 0); PG8_STAGE(PG8_SA(1, 1), a1 + hstepA, voffA);
;             PG8_WAIT_V(8); PG8_WAIT_L(0); PG8_BAR; PG8_MMA(0, 0, At, B0); PG8_MMA(0, 1, At, B1); PG8_BAR; PG8_SCHED;
;             PG8_LDA(At, 0, 1); PG8_STAGE(PG8_SB(0, 0), b2, voffB); PG8_STAGE(PG8_SB(0, 1), b2 + hstepB, voffB); PG8_STAGE(PG8_SA(0, 0), a2, voffA);
;             PG8_WAIT_V(8); PG8_WAIT_L(0); PG8_BAR; PG8_MMA(1, 0, At, B0); PG8_MMA(1, 1, At, B1); PG8_BAR; PG8_SCHED;
.LBB0_1645:
	s_waitcnt lgkmcnt(0)
	ds_read_b128 v[154:157], v182
	ds_read_b128 v[158:161], v182 offset:1024
	ds_read_b128 v[162:165], v182 offset:2048
	ds_read_b128 v[166:169], v182 offset:3072
	ds_read_b128 v[170:173], v183
	ds_read_b128 v[174:177], v183 offset:1024
	ds_read_b128 v[188:191], v183 offset:2048
	ds_read_b128 v[192:195], v183 offset:3072
	s_add_u32 s2, s8, 0xfffc0080
	s_addc_u32 s3, s9, -1
	s_cmp_eq_u32 vcc_lo, 12
	s_cselect_b32 s79, s7, s3
	s_cselect_b32 s78, s67, s2
	s_cselect_b32 s77, s69, s97
	s_cselect_b32 s76, s71, s96
	s_add_i32 m0, s83, 0xc000
	ds_read_b128 v[196:199], v184
	ds_read_b128 v[200:203], v184 offset:1024
	ds_read_b128 v[204:207], v184 offset:2048
	ds_read_b128 v[208:211], v184 offset:3072
	ds_read_b128 v[212:215], v184 offset:4096
	ds_read_b128 v[216:219], v184 offset:5120
	ds_read_b128 v[220:223], v184 offset:6144
	ds_read_b128 v[224:227], v184 offset:7168
	global_load_lds_dwordx4 v146, s[8:9]
	s_add_i32 m0, s83, 0xe000
	s_nop 0
	global_load_lds_dwordx4 v148, s[8:9]
	s_waitcnt vmcnt(8)
	s_waitcnt lgkmcnt(0)
	s_barrier
	s_setprio 1
	v_mfma_f32_16x16x32_bf16 v[124:127], v[154:157], v[196:199], v[124:127]
	v_mfma_f32_16x16x32_bf16 v[120:123], v[162:165], v[196:199], v[120:123]
	v_mfma_f32_16x16x32_bf16 v[108:111], v[154:157], v[204:207], v[108:111]
	v_mfma_f32_16x16x32_bf16 v[104:107], v[162:165], v[204:207], v[104:107]
	v_mfma_f32_16x16x32_bf16 v[92:95], v[154:157], v[212:215], v[92:95]
	v_mfma_f32_16x16x32_bf16 v[88:91], v[162:165], v[212:215], v[88:91]
	v_mfma_f32_16x16x32_bf16 v[76:79], v[154:157], v[220:223], v[76:79]
	v_mfma_f32_16x16x32_bf16 v[72:75], v[162:165], v[220:223], v[72:75]
	v_mfma_f32_16x16x32_bf16 v[124:127], v[158:161], v[200:203], v[124:127]
	v_mfma_f32_16x16x32_bf16 v[120:123], v[166:169], v[200:203], v[120:123]
	v_mfma_f32_16x16x32_bf16 v[108:111], v[158:161], v[208:211], v[108:111]
	v_mfma_f32_16x16x32_bf16 v[104:107], v[166:169], v[208:211], v[104:107]
	v_mfma_f32_16x16x32_bf16 v[92:95], v[158:161], v[216:219], v[92:95]
	v_mfma_f32_16x16x32_bf16 v[88:91], v[166:169], v[216:219], v[88:91]
	v_mfma_f32_16x16x32_bf16 v[76:79], v[158:161], v[224:227], v[76:79]
	v_mfma_f32_16x16x32_bf16 v[72:75], v[166:169], v[224:227], v[72:75]
	v_mfma_f32_16x16x32_bf16 v[116:119], v[170:173], v[196:199], v[116:119]
	v_mfma_f32_16x16x32_bf16 v[112:115], v[188:191], v[196:199], v[112:115]
	v_mfma_f32_16x16x32_bf16 v[100:103], v[170:173], v[204:207], v[100:103]
	v_mfma_f32_16x16x32_bf16 v[96:99], v[188:191], v[204:207], v[96:99]
	v_mfma_f32_16x16x32_bf16 v[84:87], v[170:173], v[212:215], v[84:87]
	v_mfma_f32_16x16x32_bf16 v[80:83], v[188:191], v[212:215], v[80:83]
	v_mfma_f32_16x16x32_bf16 v[68:71], v[170:173], v[220:223], v[68:71]
	v_mfma_f32_16x16x32_bf16 v[64:67], v[188:191], v[220:223], v[64:67]
	v_mfma_f32_16x16x32_bf16 v[116:119], v[174:177], v[200:203], v[116:119]
	v_mfma_f32_16x16x32_bf16 v[112:115], v[192:195], v[200:203], v[112:115]
	v_mfma_f32_16x16x32_bf16 v[100:103], v[174:177], v[208:211], v[100:103]
	v_mfma_f32_16x16x32_bf16 v[96:99], v[192:195], v[208:211], v[96:99]
	v_mfma_f32_16x16x32_bf16 v[84:87], v[174:177], v[216:219], v[84:87]
	v_mfma_f32_16x16x32_bf16 v[80:83], v[192:195], v[216:219], v[80:83]
	v_mfma_f32_16x16x32_bf16 v[68:71], v[174:177], v[224:227], v[68:71]
	v_mfma_f32_16x16x32_bf16 v[64:67], v[192:195], v[224:227], v[64:67]
	s_setprio 0
	s_barrier
	s_add_i32 s2, s91, s82
	s_mov_b32 m0, s2
	ds_read_b128 v[196:199], v184 offset:16384
	ds_read_b128 v[200:203], v184 offset:17408
	ds_read_b128 v[204:207], v184 offset:18432
	ds_read_b128 v[208:211], v184 offset:19456
	ds_read_b128 v[212:215], v184 offset:20480
	ds_read_b128 v[216:219], v184 offset:21504
	ds_read_b128 v[220:223], v184 offset:22528
	ds_read_b128 v[224:227], v184 offset:23552
	global_load_lds_dwordx4 v130, s[76:77]
	s_add_i32 m0, s2, 0x2000
	s_add_u32 s2, s76, 0x40000
	s_addc_u32 s3, s77, 0
	s_add_i32 vcc_hi, s92, s82
	global_load_lds_dwordx4 v134, s[76:77]
	s_mov_b32 m0, vcc_hi
	s_nop 0
	global_load_lds_dwordx4 v130, s[2:3]
	s_add_i32 m0, vcc_hi, 0x2000
	s_nop 0
	global_load_lds_dwordx4 v134, s[2:3]
	s_mov_b32 m0, s83
	s_nop 0
	global_load_lds_dwordx4 v128, s[78:79]
	s_mov_b32 m0, s84
	s_nop 0
	global_load_lds_dwordx4 v132, s[78:79]
	s_waitcnt vmcnt(8)
	s_waitcnt lgkmcnt(0)
	s_barrier
	s_setprio 1
	v_mfma_f32_16x16x32_bf16 v[60:63], v[154:157], v[196:199], v[60:63]
	v_mfma_f32_16x16x32_bf16 v[56:59], v[162:165], v[196:199], v[56:59]
	v_mfma_f32_16x16x32_bf16 v[44:47], v[154:157], v[204:207], v[44:47]
	v_mfma_f32_16x16x32_bf16 v[40:43], v[162:165], v[204:207], v[40:43]
	v_mfma_f32_16x16x32_bf16 v[28:31], v[154:157], v[212:215], v[28:31]
	v_mfma_f32_16x16x32_bf16 v[24:27], v[162:165], v[212:215], v[24:27]
	v_mfma_f32_16x16x32_bf16 v[12:15], v[154:157], v[220:223], v[12:15]
	v_mfma_f32_16x16x32_bf16 v[8:11], v[162:165], v[220:223], v[8:11]
	v_mfma_f32_16x16x32_bf16 v[60:63], v[158:161], v[200:203], v[60:63]
	v_mfma_f32_16x16x32_bf16 v[56:59], v[166:169], v[200:203], v[56:59]
	v_mfma_f32_16x16x32_bf16 v[44:47], v[158:161], v[208:211], v[44:47]
	v_mfma_f32_16x16x32_bf16 v[40:43], v[166:169], v[208:211], v[40:43]
	v_mfma_f32_16x16x32_bf16 v[28:31], v[158:161], v[216:219], v[28:31]
	v_mfma_f32_16x16x32_bf16 v[24:27], v[166:169], v[216:219], v[24:27]
	v_mfma_f32_16x16x32_bf16 v[12:15], v[158:161], v[224:227], v[12:15]
	v_mfma_f32_16x16x32_bf16 v[8:11], v[166:169], v[224:227], v[8:11]
	v_mfma_f32_16x16x32_bf16 v[52:55], v[170:173], v[196:199], v[52:55]
	v_mfma_f32_16x16x32_bf16 v[48:51], v[188:191], v[196:199], v[48:51]
	v_mfma_f32_16x16x32_bf16 v[36:39], v[170:173], v[204:207], v[36:39]
	v_mfma_f32_16x16x32_bf16 v[32:35], v[188:191], v[204:207], v[32:35]
	v_mfma_f32_16x16x32_bf16 v[20:23], v[170:173], v[212:215], v[20:23]
	v_mfma_f32_16x16x32_bf16 v[16:19], v[188:191], v[212:215], v[16:19]
	v_mfma_f32_16x16x32_bf16 v[4:7], v[170:173], v[220:223], v[4:7]
	v_mfma_f32_16x16x32_bf16 v[0:3], v[188:191], v[220:223], v[0:3]
	v_mfma_f32_16x16x32_bf16 v[52:55], v[174:177], v[200:203], v[52:55]
	v_mfma_f32_16x16x32_bf16 v[48:51], v[192:195], v[200:203], v[48:51]
	v_mfma_f32_16x16x32_bf16 v[36:39], v[174:177], v[208:211], v[36:39]
	v_mfma_f32_16x16x32_bf16 v[32:35], v[192:195], v[208:211], v[32:35]
	v_mfma_f32_16x16x32_bf16 v[20:23], v[174:177], v[216:219], v[20:23]
	v_mfma_f32_16x16x32_bf16 v[16:19], v[192:195], v[216:219], v[16:19]
	v_mfma_f32_16x16x32_bf16 v[4:7], v[174:177], v[224:227], v[4:7]
	v_mfma_f32_16x16x32_bf16 v[0:3], v[192:195], v[224:227], v[0:3]
	s_setprio 0
	s_barrier
; #define PG8_STAGE(bufoff, gbase, voff) do { _Pragma("unroll") for (int _i = 0; _i < 2; ++_i) \
;         __builtin_amdgcn_global_load_lds((const unsigned*)((const char*)(gbase) + (voff)[_i]), (PG8_LAS unsigned*)(lds + (bufoff) + ldsw + _i * 8192), 16, 0, 0); } while (0)
; #define PG8_LDA(dst, b, h) do { _Pragma("unroll") for (int m = 0; m < 4; ++m) _Pragma("unroll") for (int k = 0; k < 2; ++k) dst[m][k] = *(const PG8_LAS bf16x8*)(lds + PG8_SA(b, h) + aoff + m * 2048 + k * 1024); } while (0)
; #define PG8_LDB(dst, b, h) do { _Pragma("unroll") for (int n = 0; n < 2; ++n) _Pragma("unroll") for (int k = 0; k < 2; ++k) dst[n][k] = *(const PG8_LAS bf16x8*)(lds + PG8_SB(b, h) + boff + n * 2048 + k * 1024); } while (0)
; #define PG8_MMA(ai, bj, At, Bt) do { __builtin_amdgcn_s_setprio(1); _Pragma("unroll") for (int m = 0; m < 4; ++m) _Pragma("unroll") for (int n = 0; n < 2; ++n) _Pragma("unroll") for (int k = 0; k < 2; ++k) \
;         acc[ai][bj][m][n] = __builtin_amdgcn_mfma_f32_16x16x32_bf16(Bt[n][k], At[m][k], acc[ai][bj][m][n], 0, 0, 0); __builtin_amdgcn_s_setprio(0); } while (0)
; #define PG8_WAIT_V(n) asm volatile("s_waitcnt vmcnt(" #n ")" ::: "memory")
; #define PG8_WAIT_L(n) asm volatile("s_waitcnt lgkmcnt(" #n ")" ::: "memory")
; #define PG8_BAR __builtin_amdgcn_s_barrier()
; template <class Epi, class Sched, bool ALIGN_EPI = false, bool SP2 = false>
; __device__ __forceinline__ void gemm_phase(PG8_LAS unsigned char* lds, const Gemm g, const Sched& S, const Epi& E, int wv) {
;     ...
;         for (int t = 0; t < nt; t += 2) {
;             const bool last = (t == nt - 2);
;             const char* a1 = cA + (size_t)(t + 1) * kstep;
;             const char* a2 = last ? nA : cA + (size_t)(t + 2) * kstep; const char* b2 = last ? nB : cB + (size_t)(t + 2) * kstep;
;             const char* a3 = a2 + kstep; const char* b3 = b2 + kstep;
;     ...
;             PG8_LDB(B0, 1, 0); PG8_LDB(B1, 1, 1); PG8_SCHED; PG8_LDA(At, 1, 0); PG8_STAGE(PG8_SA(0, 1), a2 + hstepA, voffA);
;             PG8_WAIT_V(8); PG8_WAIT_L(0); PG8_BAR; PG8_MMA(0, 0, At, B0); PG8_MMA(0, 1, At, B1); PG8_BAR; PG8_SCHED;
;             PG8_LDA(At, 1, 1); PG8_STAGE(PG8_SB(1, 0), b3, voffB); PG8_STAGE(PG8_SB(1, 1), b3 + hstepB, voffB); PG8_STAGE(PG8_SA(1, 0), a3, voffA);
;             PG8_WAIT_V(8); PG8_WAIT_L(0); PG8_BAR; PG8_MMA(1, 0, At, B0); PG8_MMA(1, 1, At, B1); PG8_BAR; PG8_SCHED;
	s_add_i32 vcc_hi, 0, 0x18000
	v_add_u32_e32 v136, vcc_hi, v178
	s_add_i32 s42, 0, 0x1c000
	ds_read_b128 v[154:157], v136
	ds_read_b128 v[158:161], v136 offset:1024
	ds_read_b128 v[162:165], v136 offset:2048
	ds_read_b128 v[166:169], v136 offset:3072
	v_add_u32_e32 v136, s42, v178
	ds_read_b128 v[170:173], v136
	ds_read_b128 v[174:177], v136 offset:1024
	ds_read_b128 v[188:191], v136 offset:2048
	ds_read_b128 v[192:195], v136 offset:3072
	s_add_u32 s2, s78, 0x40000
	s_addc_u32 s3, s79, 0
	s_mov_b32 m0, s85
	ds_read_b128 v[196:199], v184 offset:32768
	ds_read_b128 v[200:203], v184 offset:33792
	ds_read_b128 v[204:207], v184 offset:34816
	ds_read_b128 v[208:211], v184 offset:35840
	ds_read_b128 v[212:215], v184 offset:36864
	ds_read_b128 v[216:219], v184 offset:37888
	ds_read_b128 v[220:223], v184 offset:38912
	ds_read_b128 v[224:227], v184 offset:39936
	global_load_lds_dwordx4 v128, s[2:3]
	s_mov_b32 m0, s86
	s_nop 0
	global_load_lds_dwordx4 v132, s[2:3]
	s_waitcnt vmcnt(8)
	s_waitcnt lgkmcnt(0)
	s_barrier
	s_setprio 1
	v_mfma_f32_16x16x32_bf16 v[124:127], v[154:157], v[196:199], v[124:127]
	v_mfma_f32_16x16x32_bf16 v[120:123], v[162:165], v[196:199], v[120:123]
	v_mfma_f32_16x16x32_bf16 v[108:111], v[154:157], v[204:207], v[108:111]
	v_mfma_f32_16x16x32_bf16 v[104:107], v[162:165], v[204:207], v[104:107]
	v_mfma_f32_16x16x32_bf16 v[92:95], v[154:157], v[212:215], v[92:95]
	v_mfma_f32_16x16x32_bf16 v[88:91], v[162:165], v[212:215], v[88:91]
	v_mfma_f32_16x16x32_bf16 v[76:79], v[154:157], v[220:223], v[76:79]
	v_mfma_f32_16x16x32_bf16 v[72:75], v[162:165], v[220:223], v[72:75]
	v_mfma_f32_16x16x32_bf16 v[124:127], v[158:161], v[200:203], v[124:127]
	v_mfma_f32_16x16x32_bf16 v[120:123], v[166:169], v[200:203], v[120:123]
	v_mfma_f32_16x16x32_bf16 v[108:111], v[158:161], v[208:211], v[108:111]
	v_mfma_f32_16x16x32_bf16 v[104:107], v[166:169], v[208:211], v[104:107]
	v_mfma_f32_16x16x32_bf16 v[92:95], v[158:161], v[216:219], v[92:95]
	v_mfma_f32_16x16x32_bf16 v[88:91], v[166:169], v[216:219], v[88:91]
	v_mfma_f32_16x16x32_bf16 v[76:79], v[158:161], v[224:227], v[76:79]
	v_mfma_f32_16x16x32_bf16 v[72:75], v[166:169], v[224:227], v[72:75]
	v_mfma_f32_16x16x32_bf16 v[116:119], v[170:173], v[196:199], v[116:119]
	v_mfma_f32_16x16x32_bf16 v[112:115], v[188:191], v[196:199], v[112:115]
	v_mfma_f32_16x16x32_bf16 v[100:103], v[170:173], v[204:207], v[100:103]
	v_mfma_f32_16x16x32_bf16 v[96:99], v[188:191], v[204:207], v[96:99]
	v_mfma_f32_16x16x32_bf16 v[84:87], v[170:173], v[212:215], v[84:87]
	v_mfma_f32_16x16x32_bf16 v[80:83], v[188:191], v[212:215], v[80:83]
	v_mfma_f32_16x16x32_bf16 v[68:71], v[170:173], v[220:223], v[68:71]
	v_mfma_f32_16x16x32_bf16 v[64:67], v[188:191], v[220:223], v[64:67]
	v_mfma_f32_16x16x32_bf16 v[116:119], v[174:177], v[200:203], v[116:119]
	v_mfma_f32_16x16x32_bf16 v[112:115], v[192:195], v[200:203], v[112:115]
	v_mfma_f32_16x16x32_bf16 v[100:103], v[174:177], v[208:211], v[100:103]
	v_mfma_f32_16x16x32_bf16 v[96:99], v[192:195], v[208:211], v[96:99]
	v_mfma_f32_16x16x32_bf16 v[84:87], v[174:177], v[216:219], v[84:87]
	v_mfma_f32_16x16x32_bf16 v[80:83], v[192:195], v[216:219], v[80:83]
	v_mfma_f32_16x16x32_bf16 v[68:71], v[174:177], v[224:227], v[68:71]
	v_mfma_f32_16x16x32_bf16 v[64:67], v[192:195], v[224:227], v[64:67]
	s_setprio 0
	s_barrier
	s_add_i32 s2, vcc_hi, s82
	s_add_u32 s98, s76, 0x80
	s_addc_u32 s99, s77, 0
	s_mov_b32 m0, s2
	ds_read_b128 v[196:199], v184 offset:49152
	ds_read_b128 v[200:203], v184 offset:50176
	ds_read_b128 v[204:207], v184 offset:51200
	ds_read_b128 v[208:211], v184 offset:52224
	ds_read_b128 v[212:215], v184 offset:53248
	ds_read_b128 v[216:219], v184 offset:54272
	ds_read_b128 v[220:223], v184 offset:55296
	ds_read_b128 v[224:227], v184 offset:56320
	global_load_lds_dwordx4 v130, s[98:99]
	s_add_i32 m0, s2, 0x2000
	s_add_u32 s2, s76, 0x40080
	s_addc_u32 s3, s77, 0
	s_add_i32 s42, s42, s82
	global_load_lds_dwordx4 v134, s[98:99]
	s_mov_b32 m0, s42
	s_nop 0
	global_load_lds_dwordx4 v130, s[2:3]
	s_add_i32 m0, s42, 0x2000
	s_nop 0
	global_load_lds_dwordx4 v134, s[2:3]
	s_add_u32 s100, s78, 0x80
	s_addc_u32 s101, s79, 0
	s_mov_b32 m0, s87
	s_nop 0
	global_load_lds_dwordx4 v128, s[100:101]
	s_mov_b32 m0, s88
	s_nop 0
	global_load_lds_dwordx4 v132, s[100:101]
	s_waitcnt vmcnt(8)
	s_waitcnt lgkmcnt(0)
	s_barrier
	s_setprio 1
	v_mfma_f32_16x16x32_bf16 v[60:63], v[154:157], v[196:199], v[60:63]
	v_mfma_f32_16x16x32_bf16 v[56:59], v[162:165], v[196:199], v[56:59]
	v_mfma_f32_16x16x32_bf16 v[44:47], v[154:157], v[204:207], v[44:47]
	v_mfma_f32_16x16x32_bf16 v[40:43], v[162:165], v[204:207], v[40:43]
	v_mfma_f32_16x16x32_bf16 v[28:31], v[154:157], v[212:215], v[28:31]
	v_mfma_f32_16x16x32_bf16 v[24:27], v[162:165], v[212:215], v[24:27]
	v_mfma_f32_16x16x32_bf16 v[12:15], v[154:157], v[220:223], v[12:15]
	v_mfma_f32_16x16x32_bf16 v[8:11], v[162:165], v[220:223], v[8:11]
	v_mfma_f32_16x16x32_bf16 v[60:63], v[158:161], v[200:203], v[60:63]
	v_mfma_f32_16x16x32_bf16 v[56:59], v[166:169], v[200:203], v[56:59]
	v_mfma_f32_16x16x32_bf16 v[44:47], v[158:161], v[208:211], v[44:47]
	v_mfma_f32_16x16x32_bf16 v[40:43], v[166:169], v[208:211], v[40:43]
	v_mfma_f32_16x16x32_bf16 v[28:31], v[158:161], v[216:219], v[28:31]
	v_mfma_f32_16x16x32_bf16 v[24:27], v[166:169], v[216:219], v[24:27]
	v_mfma_f32_16x16x32_bf16 v[12:15], v[158:161], v[224:227], v[12:15]
	v_mfma_f32_16x16x32_bf16 v[8:11], v[166:169], v[224:227], v[8:11]
	v_mfma_f32_16x16x32_bf16 v[52:55], v[170:173], v[196:199], v[52:55]
	v_mfma_f32_16x16x32_bf16 v[48:51], v[188:191], v[196:199], v[48:51]
	v_mfma_f32_16x16x32_bf16 v[36:39], v[170:173], v[204:207], v[36:39]
	v_mfma_f32_16x16x32_bf16 v[32:35], v[188:191], v[204:207], v[32:35]
	v_mfma_f32_16x16x32_bf16 v[20:23], v[170:173], v[212:215], v[20:23]
	v_mfma_f32_16x16x32_bf16 v[16:19], v[188:191], v[212:215], v[16:19]
	v_mfma_f32_16x16x32_bf16 v[4:7], v[170:173], v[220:223], v[4:7]
	v_mfma_f32_16x16x32_bf16 v[0:3], v[188:191], v[220:223], v[0:3]
	v_mfma_f32_16x16x32_bf16 v[52:55], v[174:177], v[200:203], v[52:55]
	v_mfma_f32_16x16x32_bf16 v[48:51], v[192:195], v[200:203], v[48:51]
	v_mfma_f32_16x16x32_bf16 v[36:39], v[174:177], v[208:211], v[36:39]
	v_mfma_f32_16x16x32_bf16 v[32:35], v[192:195], v[208:211], v[32:35]
	v_mfma_f32_16x16x32_bf16 v[20:23], v[174:177], v[216:219], v[20:23]
	v_mfma_f32_16x16x32_bf16 v[16:19], v[192:195], v[216:219], v[16:19]
	v_mfma_f32_16x16x32_bf16 v[4:7], v[174:177], v[224:227], v[4:7]
	v_mfma_f32_16x16x32_bf16 v[0:3], v[192:195], v[224:227], v[0:3]
	s_setprio 0
	s_add_i32 vcc_lo, vcc_lo, 2
	s_add_u32 s8, s8, 0x100
	s_addc_u32 s9, s9, 0
	s_add_u32 s96, s96, 0x100
	s_addc_u32 s97, s97, 0
	s_cmp_gt_u32 vcc_lo, 13
	s_barrier
	s_cbranch_scc0 .LBB0_1645
	s_and_b64 vcc, exec, s[56:57]
	s_cbranch_vccz .LBB0_1648
	s_barrier

; #define PG8_STAGE(bufoff, gbase, voff) do { _Pragma("unroll") for (int _i = 0; _i < 2; ++_i) \
;         __builtin_amdgcn_global_load_lds((const unsigned*)((const char*)(gbase) + (voff)[_i]), (PG8_LAS unsigned*)(lds + (bufoff) + ldsw + _i * 8192), 16, 0, 0); } while (0)
; #define PG8_LDA(dst, b, h) do { _Pragma("unroll") for (int m = 0; m < 4; ++m) _Pragma("unroll") for (int k = 0; k < 2; ++k) dst[m][k] = *(const PG8_LAS bf16x8*)(lds + PG8_SA(b, h) + aoff + m * 2048 + k * 1024); } while (0)
; #define PG8_LDB(dst, b, h) do { _Pragma("unroll") for (int n = 0; n < 2; ++n) _Pragma("unroll") for (int k = 0; k < 2; ++k) dst[n][k] = *(const PG8_LAS bf16x8*)(lds + PG8_SB(b, h) + boff + n * 2048 + k * 1024); } while (0)
; #define PG8_MMA(ai, bj, At, Bt) do { __builtin_amdgcn_s_setprio(1); _Pragma("unroll") for (int m = 0; m < 4; ++m) _Pragma("unroll") for (int n = 0; n < 2; ++n) _Pragma("unroll") for (int k = 0; k < 2; ++k) \
;         acc[ai][bj][m][n] = __builtin_amdgcn_mfma_f32_16x16x32_bf16(Bt[n][k], At[m][k], acc[ai][bj][m][n], 0, 0, 0); __builtin_amdgcn_s_setprio(0); } while (0)
; #define PG8_WAIT_V(n) asm volatile("s_waitcnt vmcnt(" #n ")" ::: "memory")
; #define PG8_BAR __builtin_amdgcn_s_barrier()
; template <class Epi, class Sched, bool ALIGN_EPI = false, bool SP2 = false>
; __device__ __forceinline__ void gemm_phase(PG8_LAS unsigned char* lds, const Gemm g, const Sched& S, const Epi& E, int wv) {
;     ...
;         for (int t = 0; t < nt; t += 2) {
;             const bool last = (t == nt - 2);
;             const char* a1 = cA + (size_t)(t + 1) * kstep;
;             const char* a2 = last ? nA : cA + (size_t)(t + 2) * kstep; const char* b2 = last ? nB : cB + (size_t)(t + 2) * kstep;
;             const char* a3 = a2 + kstep; const char* b3 = b2 + kstep;
;             if (last && has_next) S.a_ready(nxt);
;             if constexpr (SP2) {
;             PG8_LDB(B0, 0, 0); PG8_LDB(B1, 0, 1); PG8_SCHED; PG8_LDA(At, 0, 0); PG8_STAGE(PG8_SA(1, 1), a1 + hstepA, voffA);
;             PG8_WAIT_V(8); PG8_WAIT_L(0); PG8_BAR; PG8_MMA(0, 0, At, B0); PG8_MMA(0, 1, At, B1); PG8_BAR; PG8_SCHED;
;             PG8_LDA(At, 0, 1); PG8_STAGE(PG8_SB(0, 0), b2, voffB); PG8_STAGE(PG8_SB(0, 1), b2 + hstepB, voffB); PG8_STAGE(PG8_SA(0, 0), a2, voffA);
;             PG8_WAIT_V(8); PG8_WAIT_L(0); PG8_BAR; PG8_MMA(1, 0, At, B0); PG8_MMA(1, 1, At, B1); PG8_BAR; PG8_SCHED;
.LBB0_1787:
	ds_read_b128 v[152:155], v164
	ds_read_b128 v[156:159], v164 offset:1024
	ds_read_b128 v[160:163], v164 offset:2048
	ds_read_b128 v[168:171], v164 offset:3072
	ds_read_b128 v[172:175], v165
	ds_read_b128 v[176:179], v165 offset:1024
	ds_read_b128 v[180:183], v165 offset:2048
	ds_read_b128 v[184:187], v165 offset:3072
	s_add_i32 s1, s0, 2
	s_add_u32 s2, s6, 0x80
	s_addc_u32 s3, s7, 0
	s_cmp_eq_u32 s80, s0
	s_cselect_b32 s9, s45, s3
	s_cselect_b32 s8, s44, s2
	s_cselect_b32 s3, s61, s13
	s_cselect_b32 s2, s60, s12
	v_lshl_add_u64 v[220:221], s[6:7], 0, v[146:147]
	s_add_i32 m0, s71, 0xc000
	ds_read_b128 v[188:191], v166
	ds_read_b128 v[192:195], v166 offset:1024
	ds_read_b128 v[196:199], v166 offset:2048
	ds_read_b128 v[200:203], v166 offset:3072
	ds_read_b128 v[204:207], v166 offset:4096
	ds_read_b128 v[208:211], v166 offset:5120
	ds_read_b128 v[212:215], v166 offset:6144
	ds_read_b128 v[216:219], v166 offset:7168
	global_load_lds_dwordx4 v[220:221], off
	v_lshl_add_u64 v[220:221], s[6:7], 0, v[148:149]
	s_add_i32 m0, s71, 0xe000
	s_nop 0
	global_load_lds_dwordx4 v[220:221], off
	s_waitcnt vmcnt(8)
	s_waitcnt lgkmcnt(0)
	s_barrier
	s_setprio 1
	v_mfma_f32_16x16x32_bf16 v[124:127], v[152:155], v[188:191], v[124:127]
	v_mfma_f32_16x16x32_bf16 v[120:123], v[160:163], v[188:191], v[120:123]
	v_mfma_f32_16x16x32_bf16 v[108:111], v[152:155], v[196:199], v[108:111]
	v_mfma_f32_16x16x32_bf16 v[104:107], v[160:163], v[196:199], v[104:107]
	v_mfma_f32_16x16x32_bf16 v[92:95], v[152:155], v[204:207], v[92:95]
	v_mfma_f32_16x16x32_bf16 v[88:91], v[160:163], v[204:207], v[88:91]
	v_mfma_f32_16x16x32_bf16 v[76:79], v[152:155], v[212:215], v[76:79]
	v_mfma_f32_16x16x32_bf16 v[72:75], v[160:163], v[212:215], v[72:75]
	v_mfma_f32_16x16x32_bf16 v[124:127], v[156:159], v[192:195], v[124:127]
	v_mfma_f32_16x16x32_bf16 v[120:123], v[168:171], v[192:195], v[120:123]
	v_mfma_f32_16x16x32_bf16 v[108:111], v[156:159], v[200:203], v[108:111]
	v_mfma_f32_16x16x32_bf16 v[104:107], v[168:171], v[200:203], v[104:107]
	v_mfma_f32_16x16x32_bf16 v[92:95], v[156:159], v[208:211], v[92:95]
	v_mfma_f32_16x16x32_bf16 v[88:91], v[168:171], v[208:211], v[88:91]
	v_mfma_f32_16x16x32_bf16 v[76:79], v[156:159], v[216:219], v[76:79]
	v_mfma_f32_16x16x32_bf16 v[72:75], v[168:171], v[216:219], v[72:75]
	v_mfma_f32_16x16x32_bf16 v[116:119], v[172:175], v[188:191], v[116:119]
	v_mfma_f32_16x16x32_bf16 v[112:115], v[180:183], v[188:191], v[112:115]
	v_mfma_f32_16x16x32_bf16 v[100:103], v[172:175], v[196:199], v[100:103]
	v_mfma_f32_16x16x32_bf16 v[96:99], v[180:183], v[196:199], v[96:99]
	v_mfma_f32_16x16x32_bf16 v[84:87], v[172:175], v[204:207], v[84:87]
	v_mfma_f32_16x16x32_bf16 v[80:83], v[180:183], v[204:207], v[80:83]
	v_mfma_f32_16x16x32_bf16 v[68:71], v[172:175], v[212:215], v[68:71]
	v_mfma_f32_16x16x32_bf16 v[64:67], v[180:183], v[212:215], v[64:67]
	v_mfma_f32_16x16x32_bf16 v[116:119], v[176:179], v[192:195], v[116:119]
	v_mfma_f32_16x16x32_bf16 v[112:115], v[184:187], v[192:195], v[112:115]
	v_mfma_f32_16x16x32_bf16 v[100:103], v[176:179], v[200:203], v[100:103]
	v_mfma_f32_16x16x32_bf16 v[96:99], v[184:187], v[200:203], v[96:99]
	v_mfma_f32_16x16x32_bf16 v[84:87], v[176:179], v[208:211], v[84:87]
	v_mfma_f32_16x16x32_bf16 v[80:83], v[184:187], v[208:211], v[80:83]
	v_mfma_f32_16x16x32_bf16 v[68:71], v[176:179], v[216:219], v[68:71]
	v_mfma_f32_16x16x32_bf16 v[64:67], v[184:187], v[216:219], v[64:67]
	s_setprio 0
	s_barrier
	s_add_i32 s0, s88, s70
	v_lshl_add_u64 v[220:221], s[2:3], 0, v[130:131]
	s_mov_b32 m0, s0
	ds_read_b128 v[188:191], v166 offset:16384
	ds_read_b128 v[192:195], v166 offset:17408
	ds_read_b128 v[196:199], v166 offset:18432
	ds_read_b128 v[200:203], v166 offset:19456
	ds_read_b128 v[204:207], v166 offset:20480
	ds_read_b128 v[208:211], v166 offset:21504
	ds_read_b128 v[212:215], v166 offset:22528
	ds_read_b128 v[216:219], v166 offset:23552
	global_load_lds_dwordx4 v[220:221], off
	s_add_i32 m0, s0, 0x2000
	v_lshl_add_u64 v[222:223], s[2:3], 0, v[134:135]
	s_add_u32 s2, s2, s40
	s_addc_u32 s3, s3, s41
	s_add_i32 s0, s89, s70
	global_load_lds_dwordx4 v[222:223], off
	v_lshl_add_u64 v[224:225], s[2:3], 0, v[130:131]
	s_mov_b32 m0, s0
	v_lshl_add_u64 v[226:227], s[2:3], 0, v[134:135]
	global_load_lds_dwordx4 v[224:225], off
	s_add_i32 m0, s0, 0x2000
	v_lshl_add_u64 v[228:229], s[8:9], 0, v[128:129]
	global_load_lds_dwordx4 v[226:227], off
	s_mov_b32 m0, s71
	v_lshl_add_u64 v[230:231], s[8:9], 0, v[132:133]
	global_load_lds_dwordx4 v[228:229], off
	s_mov_b32 m0, s72
	s_nop 0
	global_load_lds_dwordx4 v[230:231], off
	s_waitcnt vmcnt(8)
	s_waitcnt lgkmcnt(0)
	s_barrier
; #define PG8_STAGE(bufoff, gbase, voff) do { _Pragma("unroll") for (int _i = 0; _i < 2; ++_i) \
;         __builtin_amdgcn_global_load_lds((const unsigned*)((const char*)(gbase) + (voff)[_i]), (PG8_LAS unsigned*)(lds + (bufoff) + ldsw + _i * 8192), 16, 0, 0); } while (0)
; #define PG8_LDA(dst, b, h) do { _Pragma("unroll") for (int m = 0; m < 4; ++m) _Pragma("unroll") for (int k = 0; k < 2; ++k) dst[m][k] = *(const PG8_LAS bf16x8*)(lds + PG8_SA(b, h) + aoff + m * 2048 + k * 1024); } while (0)
; #define PG8_LDB(dst, b, h) do { _Pragma("unroll") for (int n = 0; n < 2; ++n) _Pragma("unroll") for (int k = 0; k < 2; ++k) dst[n][k] = *(const PG8_LAS bf16x8*)(lds + PG8_SB(b, h) + boff + n * 2048 + k * 1024); } while (0)
; #define PG8_MMA(ai, bj, At, Bt) do { __builtin_amdgcn_s_setprio(1); _Pragma("unroll") for (int m = 0; m < 4; ++m) _Pragma("unroll") for (int n = 0; n < 2; ++n) _Pragma("unroll") for (int k = 0; k < 2; ++k) \
;         acc[ai][bj][m][n] = __builtin_amdgcn_mfma_f32_16x16x32_bf16(Bt[n][k], At[m][k], acc[ai][bj][m][n], 0, 0, 0); __builtin_amdgcn_s_setprio(0); } while (0)
; #define PG8_WAIT_V(n) asm volatile("s_waitcnt vmcnt(" #n ")" ::: "memory")
; #define PG8_WAIT_L(n) asm volatile("s_waitcnt lgkmcnt(" #n ")" ::: "memory")
; #define PG8_BAR __builtin_amdgcn_s_barrier()
; #define PG8_SCHED __builtin_amdgcn_sched_barrier(0)
; template <class Epi, class Sched, bool ALIGN_EPI = false, bool SP2 = false>
; __device__ __forceinline__ void gemm_phase(PG8_LAS unsigned char* lds, const Gemm g, const Sched& S, const Epi& E, int wv) {
;     ...
;             PG8_WAIT_V(8); PG8_WAIT_L(0); PG8_BAR; PG8_MMA(0, 0, At, B0); PG8_MMA(0, 1, At, B1); PG8_BAR; PG8_SCHED;
;             PG8_LDA(At, 0, 1); PG8_STAGE(PG8_SB(0, 0), b2, voffB); PG8_STAGE(PG8_SB(0, 1), b2 + hstepB, voffB); PG8_STAGE(PG8_SA(0, 0), a2, voffA);
;             PG8_WAIT_V(8); PG8_WAIT_L(0); PG8_BAR; PG8_MMA(1, 0, At, B0); PG8_MMA(1, 1, At, B1); PG8_BAR; PG8_SCHED;
;             PG8_LDB(B0, 1, 0); PG8_LDB(B1, 1, 1); PG8_SCHED; PG8_LDA(At, 1, 0); PG8_STAGE(PG8_SA(0, 1), a2 + hstepA, voffA);
;             PG8_WAIT_V(8); PG8_WAIT_L(0); PG8_BAR; PG8_MMA(0, 0, At, B0); PG8_MMA(0, 1, At, B1); PG8_BAR; PG8_SCHED;
	s_setprio 1
	v_mfma_f32_16x16x32_bf16 v[60:63], v[152:155], v[188:191], v[60:63]
	v_mfma_f32_16x16x32_bf16 v[56:59], v[160:163], v[188:191], v[56:59]
	v_mfma_f32_16x16x32_bf16 v[44:47], v[152:155], v[196:199], v[44:47]
	v_mfma_f32_16x16x32_bf16 v[40:43], v[160:163], v[196:199], v[40:43]
	v_mfma_f32_16x16x32_bf16 v[28:31], v[152:155], v[204:207], v[28:31]
	v_mfma_f32_16x16x32_bf16 v[24:27], v[160:163], v[204:207], v[24:27]
	v_mfma_f32_16x16x32_bf16 v[12:15], v[152:155], v[212:215], v[12:15]
	v_mfma_f32_16x16x32_bf16 v[8:11], v[160:163], v[212:215], v[8:11]
	v_mfma_f32_16x16x32_bf16 v[60:63], v[156:159], v[192:195], v[60:63]
	v_mfma_f32_16x16x32_bf16 v[56:59], v[168:171], v[192:195], v[56:59]
	v_mfma_f32_16x16x32_bf16 v[44:47], v[156:159], v[200:203], v[44:47]
	v_mfma_f32_16x16x32_bf16 v[40:43], v[168:171], v[200:203], v[40:43]
	v_mfma_f32_16x16x32_bf16 v[28:31], v[156:159], v[208:211], v[28:31]
	v_mfma_f32_16x16x32_bf16 v[24:27], v[168:171], v[208:211], v[24:27]
	v_mfma_f32_16x16x32_bf16 v[12:15], v[156:159], v[216:219], v[12:15]
	v_mfma_f32_16x16x32_bf16 v[8:11], v[168:171], v[216:219], v[8:11]
	v_mfma_f32_16x16x32_bf16 v[52:55], v[172:175], v[188:191], v[52:55]
	v_mfma_f32_16x16x32_bf16 v[48:51], v[180:183], v[188:191], v[48:51]
	v_mfma_f32_16x16x32_bf16 v[36:39], v[172:175], v[196:199], v[36:39]
	v_mfma_f32_16x16x32_bf16 v[32:35], v[180:183], v[196:199], v[32:35]
	v_mfma_f32_16x16x32_bf16 v[20:23], v[172:175], v[204:207], v[20:23]
	v_mfma_f32_16x16x32_bf16 v[16:19], v[180:183], v[204:207], v[16:19]
	v_mfma_f32_16x16x32_bf16 v[4:7], v[172:175], v[212:215], v[4:7]
	v_mfma_f32_16x16x32_bf16 v[0:3], v[180:183], v[212:215], v[0:3]
	v_mfma_f32_16x16x32_bf16 v[52:55], v[176:179], v[192:195], v[52:55]
	v_mfma_f32_16x16x32_bf16 v[48:51], v[184:187], v[192:195], v[48:51]
	v_mfma_f32_16x16x32_bf16 v[36:39], v[176:179], v[200:203], v[36:39]
	v_mfma_f32_16x16x32_bf16 v[32:35], v[184:187], v[200:203], v[32:35]
	v_mfma_f32_16x16x32_bf16 v[20:23], v[176:179], v[208:211], v[20:23]
	v_mfma_f32_16x16x32_bf16 v[16:19], v[184:187], v[208:211], v[16:19]
	v_mfma_f32_16x16x32_bf16 v[4:7], v[176:179], v[216:219], v[4:7]
	v_mfma_f32_16x16x32_bf16 v[0:3], v[184:187], v[216:219], v[0:3]
	s_setprio 0
	s_barrier
	s_add_i32 s0, 0, 0x18000
	v_add_u32_e32 v136, s0, v141
	s_add_i32 s42, 0, 0x1c000
	ds_read_b128 v[152:155], v136
	ds_read_b128 v[156:159], v136 offset:1024
	ds_read_b128 v[160:163], v136 offset:2048
	ds_read_b128 v[168:171], v136 offset:3072
	v_add_u32_e32 v136, s42, v141
	ds_read_b128 v[172:175], v136
	ds_read_b128 v[176:179], v136 offset:1024
	ds_read_b128 v[180:183], v136 offset:2048
	ds_read_b128 v[184:187], v136 offset:3072
	s_add_u32 s2, s8, s38
	s_addc_u32 s3, s9, s39
	s_mov_b32 m0, s73
	v_lshl_add_u64 v[232:233], s[2:3], 0, v[128:129]
	ds_read_b128 v[188:191], v166 offset:32768
	ds_read_b128 v[192:195], v166 offset:33792
	ds_read_b128 v[196:199], v166 offset:34816
	ds_read_b128 v[200:203], v166 offset:35840
	ds_read_b128 v[204:207], v166 offset:36864
	ds_read_b128 v[208:211], v166 offset:37888
	ds_read_b128 v[212:215], v166 offset:38912
	ds_read_b128 v[216:219], v166 offset:39936
	global_load_lds_dwordx4 v[232:233], off
	v_lshl_add_u64 v[232:233], s[2:3], 0, v[132:133]
	s_mov_b32 m0, s74
	s_nop 0
	global_load_lds_dwordx4 v[232:233], off
	s_waitcnt vmcnt(8)
	s_waitcnt lgkmcnt(0)
	s_barrier
	s_setprio 1
	v_mfma_f32_16x16x32_bf16 v[124:127], v[152:155], v[188:191], v[124:127]
	v_mfma_f32_16x16x32_bf16 v[120:123], v[160:163], v[188:191], v[120:123]
	v_mfma_f32_16x16x32_bf16 v[108:111], v[152:155], v[196:199], v[108:111]
	v_mfma_f32_16x16x32_bf16 v[104:107], v[160:163], v[196:199], v[104:107]
	v_mfma_f32_16x16x32_bf16 v[92:95], v[152:155], v[204:207], v[92:95]
	v_mfma_f32_16x16x32_bf16 v[88:91], v[160:163], v[204:207], v[88:91]
	v_mfma_f32_16x16x32_bf16 v[76:79], v[152:155], v[212:215], v[76:79]
	v_mfma_f32_16x16x32_bf16 v[72:75], v[160:163], v[212:215], v[72:75]
	v_mfma_f32_16x16x32_bf16 v[124:127], v[156:159], v[192:195], v[124:127]
	v_mfma_f32_16x16x32_bf16 v[120:123], v[168:171], v[192:195], v[120:123]
	v_mfma_f32_16x16x32_bf16 v[108:111], v[156:159], v[200:203], v[108:111]
	v_mfma_f32_16x16x32_bf16 v[104:107], v[168:171], v[200:203], v[104:107]
	v_mfma_f32_16x16x32_bf16 v[92:95], v[156:159], v[208:211], v[92:95]
	v_mfma_f32_16x16x32_bf16 v[88:91], v[168:171], v[208:211], v[88:91]
	v_mfma_f32_16x16x32_bf16 v[76:79], v[156:159], v[216:219], v[76:79]
	v_mfma_f32_16x16x32_bf16 v[72:75], v[168:171], v[216:219], v[72:75]
	v_mfma_f32_16x16x32_bf16 v[116:119], v[172:175], v[188:191], v[116:119]
	v_mfma_f32_16x16x32_bf16 v[112:115], v[180:183], v[188:191], v[112:115]
	v_mfma_f32_16x16x32_bf16 v[100:103], v[172:175], v[196:199], v[100:103]
	v_mfma_f32_16x16x32_bf16 v[96:99], v[180:183], v[196:199], v[96:99]
	v_mfma_f32_16x16x32_bf16 v[84:87], v[172:175], v[204:207], v[84:87]
	v_mfma_f32_16x16x32_bf16 v[80:83], v[180:183], v[204:207], v[80:83]
	v_mfma_f32_16x16x32_bf16 v[68:71], v[172:175], v[212:215], v[68:71]
	v_mfma_f32_16x16x32_bf16 v[64:67], v[180:183], v[212:215], v[64:67]
	v_mfma_f32_16x16x32_bf16 v[116:119], v[176:179], v[192:195], v[116:119]
	v_mfma_f32_16x16x32_bf16 v[112:115], v[184:187], v[192:195], v[112:115]
	v_mfma_f32_16x16x32_bf16 v[100:103], v[176:179], v[200:203], v[100:103]
	v_mfma_f32_16x16x32_bf16 v[96:99], v[184:187], v[200:203], v[96:99]
	v_mfma_f32_16x16x32_bf16 v[84:87], v[176:179], v[208:211], v[84:87]
	v_mfma_f32_16x16x32_bf16 v[80:83], v[184:187], v[208:211], v[80:83]
	v_mfma_f32_16x16x32_bf16 v[68:71], v[176:179], v[216:219], v[68:71]
	v_mfma_f32_16x16x32_bf16 v[64:67], v[184:187], v[216:219], v[64:67]
	s_setprio 0
	s_barrier
; #define PG8_STAGE(bufoff, gbase, voff) do { _Pragma("unroll") for (int _i = 0; _i < 2; ++_i) \
;         __builtin_amdgcn_global_load_lds((const unsigned*)((const char*)(gbase) + (voff)[_i]), (PG8_LAS unsigned*)(lds + (bufoff) + ldsw + _i * 8192), 16, 0, 0); } while (0)
; #define PG8_LDA(dst, b, h) do { _Pragma("unroll") for (int m = 0; m < 4; ++m) _Pragma("unroll") for (int k = 0; k < 2; ++k) dst[m][k] = *(const PG8_LAS bf16x8*)(lds + PG8_SA(b, h) + aoff + m * 2048 + k * 1024); } while (0)
; #define PG8_MMA(ai, bj, At, Bt) do { __builtin_amdgcn_s_setprio(1); _Pragma("unroll") for (int m = 0; m < 4; ++m) _Pragma("unroll") for (int n = 0; n < 2; ++n) _Pragma("unroll") for (int k = 0; k < 2; ++k) \
;         acc[ai][bj][m][n] = __builtin_amdgcn_mfma_f32_16x16x32_bf16(Bt[n][k], At[m][k], acc[ai][bj][m][n], 0, 0, 0); __builtin_amdgcn_s_setprio(0); } while (0)
; #define PG8_WAIT_V(n) asm volatile("s_waitcnt vmcnt(" #n ")" ::: "memory")
; #define PG8_WAIT_L(n) asm volatile("s_waitcnt lgkmcnt(" #n ")" ::: "memory")
; #define PG8_BAR __builtin_amdgcn_s_barrier()
; #define PG8_SCHED __builtin_amdgcn_sched_barrier(0)
; template <class Epi, class Sched, bool ALIGN_EPI = false, bool SP2 = false>
; __device__ __forceinline__ void gemm_phase(PG8_LAS unsigned char* lds, const Gemm g, const Sched& S, const Epi& E, int wv) {
;     ...
;         for (int t = 0; t < nt; t += 2) {
;             const bool last = (t == nt - 2);
;             const char* a1 = cA + (size_t)(t + 1) * kstep;
;             const char* a2 = last ? nA : cA + (size_t)(t + 2) * kstep; const char* b2 = last ? nB : cB + (size_t)(t + 2) * kstep;
;             const char* a3 = a2 + kstep; const char* b3 = b2 + kstep;
;     ...
;             PG8_LDA(At, 1, 1); PG8_STAGE(PG8_SB(1, 0), b3, voffB); PG8_STAGE(PG8_SB(1, 1), b3 + hstepB, voffB); PG8_STAGE(PG8_SA(1, 0), a3, voffA);
;             PG8_WAIT_V(8); PG8_WAIT_L(0); PG8_BAR; PG8_MMA(1, 0, At, B0); PG8_MMA(1, 1, At, B1); PG8_BAR; PG8_SCHED;
	s_add_i32 s0, s0, s70
	v_lshl_add_u64 v[220:221], v[220:221], 0, s[54:55]
	s_mov_b32 m0, s0
	ds_read_b128 v[188:191], v166 offset:49152
	ds_read_b128 v[192:195], v166 offset:50176
	ds_read_b128 v[196:199], v166 offset:51200
	ds_read_b128 v[200:203], v166 offset:52224
	ds_read_b128 v[204:207], v166 offset:53248
	ds_read_b128 v[208:211], v166 offset:54272
	ds_read_b128 v[212:215], v166 offset:55296
	ds_read_b128 v[216:219], v166 offset:56320
	global_load_lds_dwordx4 v[220:221], off
	v_lshl_add_u64 v[220:221], v[222:223], 0, s[54:55]
	s_add_i32 m0, s0, 0x2000
	s_add_i32 s0, s42, s70
	global_load_lds_dwordx4 v[220:221], off
	v_lshl_add_u64 v[220:221], v[224:225], 0, s[54:55]
	s_mov_b32 m0, s0
	s_nop 0
	global_load_lds_dwordx4 v[220:221], off
	v_lshl_add_u64 v[220:221], v[226:227], 0, s[54:55]
	s_add_i32 m0, s0, 0x2000
	s_nop 0
	global_load_lds_dwordx4 v[220:221], off
	v_lshl_add_u64 v[220:221], v[228:229], 0, s[54:55]
	s_mov_b32 m0, s76
	s_nop 0
	global_load_lds_dwordx4 v[220:221], off
	v_lshl_add_u64 v[220:221], v[230:231], 0, s[54:55]
	s_mov_b32 m0, s77
	s_nop 0
	global_load_lds_dwordx4 v[220:221], off
	s_waitcnt vmcnt(8)
	s_waitcnt lgkmcnt(0)
	s_barrier
	s_setprio 1
	v_mfma_f32_16x16x32_bf16 v[60:63], v[152:155], v[188:191], v[60:63]
	v_mfma_f32_16x16x32_bf16 v[56:59], v[160:163], v[188:191], v[56:59]
	v_mfma_f32_16x16x32_bf16 v[44:47], v[152:155], v[196:199], v[44:47]
	v_mfma_f32_16x16x32_bf16 v[40:43], v[160:163], v[196:199], v[40:43]
	v_mfma_f32_16x16x32_bf16 v[28:31], v[152:155], v[204:207], v[28:31]
	v_mfma_f32_16x16x32_bf16 v[24:27], v[160:163], v[204:207], v[24:27]
	v_mfma_f32_16x16x32_bf16 v[12:15], v[152:155], v[212:215], v[12:15]
	v_mfma_f32_16x16x32_bf16 v[8:11], v[160:163], v[212:215], v[8:11]
	v_mfma_f32_16x16x32_bf16 v[60:63], v[156:159], v[192:195], v[60:63]
	v_mfma_f32_16x16x32_bf16 v[56:59], v[168:171], v[192:195], v[56:59]
	v_mfma_f32_16x16x32_bf16 v[44:47], v[156:159], v[200:203], v[44:47]
	v_mfma_f32_16x16x32_bf16 v[40:43], v[168:171], v[200:203], v[40:43]
	v_mfma_f32_16x16x32_bf16 v[28:31], v[156:159], v[208:211], v[28:31]
	v_mfma_f32_16x16x32_bf16 v[24:27], v[168:171], v[208:211], v[24:27]
	v_mfma_f32_16x16x32_bf16 v[12:15], v[156:159], v[216:219], v[12:15]
	v_mfma_f32_16x16x32_bf16 v[8:11], v[168:171], v[216:219], v[8:11]
	v_mfma_f32_16x16x32_bf16 v[52:55], v[172:175], v[188:191], v[52:55]
	v_mfma_f32_16x16x32_bf16 v[48:51], v[180:183], v[188:191], v[48:51]
	v_mfma_f32_16x16x32_bf16 v[36:39], v[172:175], v[196:199], v[36:39]
	v_mfma_f32_16x16x32_bf16 v[32:35], v[180:183], v[196:199], v[32:35]
	v_mfma_f32_16x16x32_bf16 v[20:23], v[172:175], v[204:207], v[20:23]
	v_mfma_f32_16x16x32_bf16 v[16:19], v[180:183], v[204:207], v[16:19]
	v_mfma_f32_16x16x32_bf16 v[4:7], v[172:175], v[212:215], v[4:7]
	v_mfma_f32_16x16x32_bf16 v[0:3], v[180:183], v[212:215], v[0:3]
	v_mfma_f32_16x16x32_bf16 v[52:55], v[176:179], v[192:195], v[52:55]
	v_mfma_f32_16x16x32_bf16 v[48:51], v[184:187], v[192:195], v[48:51]
	v_mfma_f32_16x16x32_bf16 v[36:39], v[176:179], v[200:203], v[36:39]
	v_mfma_f32_16x16x32_bf16 v[32:35], v[184:187], v[200:203], v[32:35]
	v_mfma_f32_16x16x32_bf16 v[20:23], v[176:179], v[208:211], v[20:23]
	v_mfma_f32_16x16x32_bf16 v[16:19], v[184:187], v[208:211], v[16:19]
	v_mfma_f32_16x16x32_bf16 v[4:7], v[176:179], v[216:219], v[4:7]
	v_mfma_f32_16x16x32_bf16 v[0:3], v[184:187], v[216:219], v[0:3]
	s_setprio 0
	s_add_u32 s6, s6, 0x100
	s_addc_u32 s7, s7, 0
	s_add_u32 s12, s12, 0x100
	s_addc_u32 s13, s13, 0
	s_cmp_ge_i32 s1, s78
	s_mov_b32 s0, s1
	s_barrier
	s_cbranch_scc0 .LBB0_1787

; #define PG8_STAGE(bufoff, gbase, voff) do { _Pragma("unroll") for (int _i = 0; _i < 2; ++_i) \
;         __builtin_amdgcn_global_load_lds((const unsigned*)((const char*)(gbase) + (voff)[_i]), (PG8_LAS unsigned*)(lds + (bufoff) + ldsw + _i * 8192), 16, 0, 0); } while (0)
; #define PG8_LDA(dst, b, h) do { _Pragma("unroll") for (int m = 0; m < 4; ++m) _Pragma("unroll") for (int k = 0; k < 2; ++k) dst[m][k] = *(const PG8_LAS bf16x8*)(lds + PG8_SA(b, h) + aoff + m * 2048 + k * 1024); } while (0)
; #define PG8_LDB(dst, b, h) do { _Pragma("unroll") for (int n = 0; n < 2; ++n) _Pragma("unroll") for (int k = 0; k < 2; ++k) dst[n][k] = *(const PG8_LAS bf16x8*)(lds + PG8_SB(b, h) + boff + n * 2048 + k * 1024); } while (0)
; #define PG8_MMA(ai, bj, At, Bt) do { __builtin_amdgcn_s_setprio(1); _Pragma("unroll") for (int m = 0; m < 4; ++m) _Pragma("unroll") for (int n = 0; n < 2; ++n) _Pragma("unroll") for (int k = 0; k < 2; ++k) \
;         acc[ai][bj][m][n] = __builtin_amdgcn_mfma_f32_16x16x32_bf16(Bt[n][k], At[m][k], acc[ai][bj][m][n], 0, 0, 0); __builtin_amdgcn_s_setprio(0); } while (0)
; #define PG8_WAIT_V(n) asm volatile("s_waitcnt vmcnt(" #n ")" ::: "memory")
; #define PG8_BAR __builtin_amdgcn_s_barrier()
; template <class Epi, class Sched, bool ALIGN_EPI = false, bool SP2 = false>
; __device__ __forceinline__ void gemm_phase(PG8_LAS unsigned char* lds, const Gemm g, const Sched& S, const Epi& E, int wv) {
;     ...
;         for (int t = 0; t < nt; t += 2) {
;             const bool last = (t == nt - 2);
;             const char* a1 = cA + (size_t)(t + 1) * kstep;
;             const char* a2 = last ? nA : cA + (size_t)(t + 2) * kstep; const char* b2 = last ? nB : cB + (size_t)(t + 2) * kstep;
;             const char* a3 = a2 + kstep; const char* b3 = b2 + kstep;
;             if (last && has_next) S.a_ready(nxt);
;             if constexpr (SP2) {
;             PG8_LDB(B0, 0, 0); PG8_LDB(B1, 0, 1); PG8_SCHED; PG8_LDA(At, 0, 0); PG8_STAGE(PG8_SA(1, 1), a1 + hstepA, voffA);
;             PG8_WAIT_V(8); PG8_WAIT_L(0); PG8_BAR; PG8_MMA(0, 0, At, B0); PG8_MMA(0, 1, At, B1); PG8_BAR; PG8_SCHED;
;             PG8_LDA(At, 0, 1); PG8_STAGE(PG8_SB(0, 0), b2, voffB); PG8_STAGE(PG8_SB(0, 1), b2 + hstepB, voffB); PG8_STAGE(PG8_SA(0, 0), a2, voffA);
;             PG8_WAIT_V(8); PG8_WAIT_L(0); PG8_BAR; PG8_MMA(1, 0, At, B0); PG8_MMA(1, 1, At, B1); PG8_BAR; PG8_SCHED;
.LBB0_1874:
	ds_read_b128 v[128:131], v202
	ds_read_b128 v[132:135], v202 offset:1024
	ds_read_b128 v[136:139], v202 offset:2048
	ds_read_b128 v[140:143], v202 offset:3072
	ds_read_b128 v[144:147], v203
	ds_read_b128 v[148:151], v203 offset:1024
	ds_read_b128 v[178:181], v203 offset:2048
	ds_read_b128 v[182:185], v203 offset:3072
	s_add_i32 s1, s0, 2
	s_add_u32 s2, s8, 0x80
	s_addc_u32 s3, s9, 0
	s_cmp_eq_u32 s78, s0
	s_cselect_b32 s63, s43, s3
	s_cselect_b32 s62, s42, s2
	s_cselect_b32 s3, s61, s65
	s_cselect_b32 s2, s60, s64
	v_lshl_add_u64 v[196:197], s[8:9], 0, v[168:169]
	s_add_i32 m0, s71, 0xc000
	ds_read_b128 v[186:189], v204
	ds_read_b128 v[190:193], v204 offset:1024
	ds_read_b128 v[206:209], v204 offset:2048
	ds_read_b128 v[210:213], v204 offset:3072
	ds_read_b128 v[214:217], v204 offset:4096
	ds_read_b128 v[218:221], v204 offset:5120
	ds_read_b128 v[222:225], v204 offset:6144
	ds_read_b128 v[226:229], v204 offset:7168
	global_load_lds_dwordx4 v[196:197], off
	v_lshl_add_u64 v[196:197], s[8:9], 0, v[170:171]
	s_add_i32 m0, s71, 0xe000
	s_nop 0
	global_load_lds_dwordx4 v[196:197], off
	s_waitcnt vmcnt(8)
	s_waitcnt lgkmcnt(0)
	s_barrier
	s_setprio 1
	v_mfma_f32_16x16x32_bf16 v[56:59], v[128:131], v[186:189], v[56:59]
	v_mfma_f32_16x16x32_bf16 v[60:63], v[136:139], v[186:189], v[60:63]
	v_mfma_f32_16x16x32_bf16 v[52:55], v[128:131], v[206:209], v[52:55]
	v_mfma_f32_16x16x32_bf16 v[48:51], v[136:139], v[206:209], v[48:51]
	v_mfma_f32_16x16x32_bf16 v[44:47], v[128:131], v[214:217], v[44:47]
	v_mfma_f32_16x16x32_bf16 v[40:43], v[136:139], v[214:217], v[40:43]
	v_mfma_f32_16x16x32_bf16 v[36:39], v[128:131], v[222:225], v[36:39]
	v_mfma_f32_16x16x32_bf16 v[32:35], v[136:139], v[222:225], v[32:35]
	v_mfma_f32_16x16x32_bf16 v[56:59], v[132:135], v[190:193], v[56:59]
	v_mfma_f32_16x16x32_bf16 v[60:63], v[140:143], v[190:193], v[60:63]
	v_mfma_f32_16x16x32_bf16 v[52:55], v[132:135], v[210:213], v[52:55]
	v_mfma_f32_16x16x32_bf16 v[48:51], v[140:143], v[210:213], v[48:51]
	v_mfma_f32_16x16x32_bf16 v[44:47], v[132:135], v[218:221], v[44:47]
	v_mfma_f32_16x16x32_bf16 v[40:43], v[140:143], v[218:221], v[40:43]
	v_mfma_f32_16x16x32_bf16 v[36:39], v[132:135], v[226:229], v[36:39]
	v_mfma_f32_16x16x32_bf16 v[32:35], v[140:143], v[226:229], v[32:35]
	v_mfma_f32_16x16x32_bf16 v[124:127], v[144:147], v[186:189], v[124:127]
	v_mfma_f32_16x16x32_bf16 v[120:123], v[178:181], v[186:189], v[120:123]
	v_mfma_f32_16x16x32_bf16 v[116:119], v[144:147], v[206:209], v[116:119]
	v_mfma_f32_16x16x32_bf16 v[112:115], v[178:181], v[206:209], v[112:115]
	v_mfma_f32_16x16x32_bf16 v[108:111], v[144:147], v[214:217], v[108:111]
	v_mfma_f32_16x16x32_bf16 v[104:107], v[178:181], v[214:217], v[104:107]
	v_mfma_f32_16x16x32_bf16 v[100:103], v[144:147], v[222:225], v[100:103]
	v_mfma_f32_16x16x32_bf16 v[96:99], v[178:181], v[222:225], v[96:99]
	v_mfma_f32_16x16x32_bf16 v[124:127], v[148:151], v[190:193], v[124:127]
	v_mfma_f32_16x16x32_bf16 v[120:123], v[182:185], v[190:193], v[120:123]
	v_mfma_f32_16x16x32_bf16 v[116:119], v[148:151], v[210:213], v[116:119]
	v_mfma_f32_16x16x32_bf16 v[112:115], v[182:185], v[210:213], v[112:115]
	v_mfma_f32_16x16x32_bf16 v[108:111], v[148:151], v[218:221], v[108:111]
	v_mfma_f32_16x16x32_bf16 v[104:107], v[182:185], v[218:221], v[104:107]
	v_mfma_f32_16x16x32_bf16 v[100:103], v[148:151], v[226:229], v[100:103]
	v_mfma_f32_16x16x32_bf16 v[96:99], v[182:185], v[226:229], v[96:99]
	s_setprio 0
	s_barrier
	s_add_i32 s0, s85, s70
	v_lshl_add_u64 v[196:197], s[2:3], 0, v[154:155]
	s_mov_b32 m0, s0
	ds_read_b128 v[186:189], v204 offset:16384
	ds_read_b128 v[190:193], v204 offset:17408
	ds_read_b128 v[206:209], v204 offset:18432
	ds_read_b128 v[210:213], v204 offset:19456
	ds_read_b128 v[214:217], v204 offset:20480
	ds_read_b128 v[218:221], v204 offset:21504
	ds_read_b128 v[222:225], v204 offset:22528
	ds_read_b128 v[226:229], v204 offset:23552
	global_load_lds_dwordx4 v[196:197], off
	s_add_i32 m0, s0, 0x2000
	v_lshl_add_u64 v[230:231], s[2:3], 0, v[158:159]
	s_add_u32 s2, s2, s40
	s_addc_u32 s3, s3, s41
	s_add_i32 s0, s86, s70
	global_load_lds_dwordx4 v[230:231], off
	v_lshl_add_u64 v[232:233], s[2:3], 0, v[154:155]
	s_mov_b32 m0, s0
	v_lshl_add_u64 v[234:235], s[2:3], 0, v[158:159]
	global_load_lds_dwordx4 v[232:233], off
	s_add_i32 m0, s0, 0x2000
	v_lshl_add_u64 v[236:237], s[62:63], 0, v[152:153]
	global_load_lds_dwordx4 v[234:235], off
	s_mov_b32 m0, s71
	v_lshl_add_u64 v[238:239], s[62:63], 0, v[156:157]
	global_load_lds_dwordx4 v[236:237], off
	s_mov_b32 m0, s72
	s_nop 0
	global_load_lds_dwordx4 v[238:239], off
	s_waitcnt vmcnt(8)
	s_waitcnt lgkmcnt(0)
	s_barrier
; #define PG8_STAGE(bufoff, gbase, voff) do { _Pragma("unroll") for (int _i = 0; _i < 2; ++_i) \
;         __builtin_amdgcn_global_load_lds((const unsigned*)((const char*)(gbase) + (voff)[_i]), (PG8_LAS unsigned*)(lds + (bufoff) + ldsw + _i * 8192), 16, 0, 0); } while (0)
; #define PG8_LDA(dst, b, h) do { _Pragma("unroll") for (int m = 0; m < 4; ++m) _Pragma("unroll") for (int k = 0; k < 2; ++k) dst[m][k] = *(const PG8_LAS bf16x8*)(lds + PG8_SA(b, h) + aoff + m * 2048 + k * 1024); } while (0)
; #define PG8_LDB(dst, b, h) do { _Pragma("unroll") for (int n = 0; n < 2; ++n) _Pragma("unroll") for (int k = 0; k < 2; ++k) dst[n][k] = *(const PG8_LAS bf16x8*)(lds + PG8_SB(b, h) + boff + n * 2048 + k * 1024); } while (0)
; #define PG8_MMA(ai, bj, At, Bt) do { __builtin_amdgcn_s_setprio(1); _Pragma("unroll") for (int m = 0; m < 4; ++m) _Pragma("unroll") for (int n = 0; n < 2; ++n) _Pragma("unroll") for (int k = 0; k < 2; ++k) \
;         acc[ai][bj][m][n] = __builtin_amdgcn_mfma_f32_16x16x32_bf16(Bt[n][k], At[m][k], acc[ai][bj][m][n], 0, 0, 0); __builtin_amdgcn_s_setprio(0); } while (0)
; #define PG8_WAIT_V(n) asm volatile("s_waitcnt vmcnt(" #n ")" ::: "memory")
; #define PG8_WAIT_L(n) asm volatile("s_waitcnt lgkmcnt(" #n ")" ::: "memory")
; #define PG8_BAR __builtin_amdgcn_s_barrier()
; #define PG8_SCHED __builtin_amdgcn_sched_barrier(0)
; template <class Epi, class Sched, bool ALIGN_EPI = false, bool SP2 = false>
; __device__ __forceinline__ void gemm_phase(PG8_LAS unsigned char* lds, const Gemm g, const Sched& S, const Epi& E, int wv) {
;     ...
;             PG8_WAIT_V(8); PG8_WAIT_L(0); PG8_BAR; PG8_MMA(0, 0, At, B0); PG8_MMA(0, 1, At, B1); PG8_BAR; PG8_SCHED;
;             PG8_LDA(At, 0, 1); PG8_STAGE(PG8_SB(0, 0), b2, voffB); PG8_STAGE(PG8_SB(0, 1), b2 + hstepB, voffB); PG8_STAGE(PG8_SA(0, 0), a2, voffA);
;             PG8_WAIT_V(8); PG8_WAIT_L(0); PG8_BAR; PG8_MMA(1, 0, At, B0); PG8_MMA(1, 1, At, B1); PG8_BAR; PG8_SCHED;
;             PG8_LDB(B0, 1, 0); PG8_LDB(B1, 1, 1); PG8_SCHED; PG8_LDA(At, 1, 0); PG8_STAGE(PG8_SA(0, 1), a2 + hstepA, voffA);
;             PG8_WAIT_V(8); PG8_WAIT_L(0); PG8_BAR; PG8_MMA(0, 0, At, B0); PG8_MMA(0, 1, At, B1); PG8_BAR; PG8_SCHED;
	s_setprio 1
	v_mfma_f32_16x16x32_bf16 v[28:31], v[128:131], v[186:189], v[28:31]
	v_mfma_f32_16x16x32_bf16 v[24:27], v[136:139], v[186:189], v[24:27]
	v_mfma_f32_16x16x32_bf16 v[20:23], v[128:131], v[206:209], v[20:23]
	v_mfma_f32_16x16x32_bf16 v[16:19], v[136:139], v[206:209], v[16:19]
	v_mfma_f32_16x16x32_bf16 v[12:15], v[128:131], v[214:217], v[12:15]
	v_mfma_f32_16x16x32_bf16 v[8:11], v[136:139], v[214:217], v[8:11]
	v_mfma_f32_16x16x32_bf16 v[4:7], v[128:131], v[222:225], v[4:7]
	v_mfma_f32_16x16x32_bf16 v[0:3], v[136:139], v[222:225], v[0:3]
	v_mfma_f32_16x16x32_bf16 v[28:31], v[132:135], v[190:193], v[28:31]
	v_mfma_f32_16x16x32_bf16 v[24:27], v[140:143], v[190:193], v[24:27]
	v_mfma_f32_16x16x32_bf16 v[20:23], v[132:135], v[210:213], v[20:23]
	v_mfma_f32_16x16x32_bf16 v[16:19], v[140:143], v[210:213], v[16:19]
	v_mfma_f32_16x16x32_bf16 v[12:15], v[132:135], v[218:221], v[12:15]
	v_mfma_f32_16x16x32_bf16 v[8:11], v[140:143], v[218:221], v[8:11]
	v_mfma_f32_16x16x32_bf16 v[4:7], v[132:135], v[226:229], v[4:7]
	v_mfma_f32_16x16x32_bf16 v[0:3], v[140:143], v[226:229], v[0:3]
	v_mfma_f32_16x16x32_bf16 v[92:95], v[144:147], v[186:189], v[92:95]
	v_mfma_f32_16x16x32_bf16 v[88:91], v[178:181], v[186:189], v[88:91]
	v_mfma_f32_16x16x32_bf16 v[84:87], v[144:147], v[206:209], v[84:87]
	v_mfma_f32_16x16x32_bf16 v[80:83], v[178:181], v[206:209], v[80:83]
	v_mfma_f32_16x16x32_bf16 v[76:79], v[144:147], v[214:217], v[76:79]
	v_mfma_f32_16x16x32_bf16 v[72:75], v[178:181], v[214:217], v[72:75]
	v_mfma_f32_16x16x32_bf16 v[68:71], v[144:147], v[222:225], v[68:71]
	v_mfma_f32_16x16x32_bf16 v[64:67], v[178:181], v[222:225], v[64:67]
	v_mfma_f32_16x16x32_bf16 v[92:95], v[148:151], v[190:193], v[92:95]
	v_mfma_f32_16x16x32_bf16 v[88:91], v[182:185], v[190:193], v[88:91]
	v_mfma_f32_16x16x32_bf16 v[84:87], v[148:151], v[210:213], v[84:87]
	v_mfma_f32_16x16x32_bf16 v[80:83], v[182:185], v[210:213], v[80:83]
	v_mfma_f32_16x16x32_bf16 v[76:79], v[148:151], v[218:221], v[76:79]
	v_mfma_f32_16x16x32_bf16 v[72:75], v[182:185], v[218:221], v[72:75]
	v_mfma_f32_16x16x32_bf16 v[68:71], v[148:151], v[226:229], v[68:71]
	v_mfma_f32_16x16x32_bf16 v[64:67], v[182:185], v[226:229], v[64:67]
	s_setprio 0
	s_barrier
	s_add_i32 s0, 0, 0x18000
	s_add_i32 s94, 0, 0x1c000
	v_add_u32_e32 v140, s0, v195
	v_add_u32_e32 v177, s94, v195
	ds_read_b128 v[128:131], v140
	ds_read_b128 v[132:135], v140 offset:1024
	ds_read_b128 v[136:139], v140 offset:2048
	ds_read_b128 v[140:143], v140 offset:3072
	ds_read_b128 v[144:147], v177
	ds_read_b128 v[148:151], v177 offset:1024
	ds_read_b128 v[178:181], v177 offset:2048
	ds_read_b128 v[182:185], v177 offset:3072
	s_add_u32 s2, s62, s38
	s_addc_u32 s3, s63, s39
	s_mov_b32 m0, s73
	v_lshl_add_u64 v[240:241], s[2:3], 0, v[152:153]
	ds_read_b128 v[186:189], v204 offset:32768
	ds_read_b128 v[190:193], v204 offset:33792
	ds_read_b128 v[206:209], v204 offset:34816
	ds_read_b128 v[210:213], v204 offset:35840
	ds_read_b128 v[214:217], v204 offset:36864
	ds_read_b128 v[218:221], v204 offset:37888
	ds_read_b128 v[222:225], v204 offset:38912
	ds_read_b128 v[226:229], v204 offset:39936
	global_load_lds_dwordx4 v[240:241], off
	v_lshl_add_u64 v[240:241], s[2:3], 0, v[156:157]
	s_mov_b32 m0, s74
	s_nop 0
	global_load_lds_dwordx4 v[240:241], off
	s_waitcnt vmcnt(8)
	s_waitcnt lgkmcnt(0)
	s_barrier
	s_setprio 1
	v_mfma_f32_16x16x32_bf16 v[56:59], v[128:131], v[186:189], v[56:59]
	v_mfma_f32_16x16x32_bf16 v[60:63], v[136:139], v[186:189], v[60:63]
	v_mfma_f32_16x16x32_bf16 v[52:55], v[128:131], v[206:209], v[52:55]
	v_mfma_f32_16x16x32_bf16 v[48:51], v[136:139], v[206:209], v[48:51]
	v_mfma_f32_16x16x32_bf16 v[44:47], v[128:131], v[214:217], v[44:47]
	v_mfma_f32_16x16x32_bf16 v[40:43], v[136:139], v[214:217], v[40:43]
	v_mfma_f32_16x16x32_bf16 v[36:39], v[128:131], v[222:225], v[36:39]
	v_mfma_f32_16x16x32_bf16 v[32:35], v[136:139], v[222:225], v[32:35]
	v_mfma_f32_16x16x32_bf16 v[56:59], v[132:135], v[190:193], v[56:59]
	v_mfma_f32_16x16x32_bf16 v[60:63], v[140:143], v[190:193], v[60:63]
	v_mfma_f32_16x16x32_bf16 v[52:55], v[132:135], v[210:213], v[52:55]
	v_mfma_f32_16x16x32_bf16 v[48:51], v[140:143], v[210:213], v[48:51]
	v_mfma_f32_16x16x32_bf16 v[44:47], v[132:135], v[218:221], v[44:47]
	v_mfma_f32_16x16x32_bf16 v[40:43], v[140:143], v[218:221], v[40:43]
	v_mfma_f32_16x16x32_bf16 v[36:39], v[132:135], v[226:229], v[36:39]
	v_mfma_f32_16x16x32_bf16 v[32:35], v[140:143], v[226:229], v[32:35]
	v_mfma_f32_16x16x32_bf16 v[124:127], v[144:147], v[186:189], v[124:127]
	v_mfma_f32_16x16x32_bf16 v[120:123], v[178:181], v[186:189], v[120:123]
	v_mfma_f32_16x16x32_bf16 v[116:119], v[144:147], v[206:209], v[116:119]
	v_mfma_f32_16x16x32_bf16 v[112:115], v[178:181], v[206:209], v[112:115]
	v_mfma_f32_16x16x32_bf16 v[108:111], v[144:147], v[214:217], v[108:111]
	v_mfma_f32_16x16x32_bf16 v[104:107], v[178:181], v[214:217], v[104:107]
	v_mfma_f32_16x16x32_bf16 v[100:103], v[144:147], v[222:225], v[100:103]
	v_mfma_f32_16x16x32_bf16 v[96:99], v[178:181], v[222:225], v[96:99]
	v_mfma_f32_16x16x32_bf16 v[124:127], v[148:151], v[190:193], v[124:127]
	v_mfma_f32_16x16x32_bf16 v[120:123], v[182:185], v[190:193], v[120:123]
	v_mfma_f32_16x16x32_bf16 v[116:119], v[148:151], v[210:213], v[116:119]
	v_mfma_f32_16x16x32_bf16 v[112:115], v[182:185], v[210:213], v[112:115]
	v_mfma_f32_16x16x32_bf16 v[108:111], v[148:151], v[218:221], v[108:111]
	v_mfma_f32_16x16x32_bf16 v[104:107], v[182:185], v[218:221], v[104:107]
	v_mfma_f32_16x16x32_bf16 v[100:103], v[148:151], v[226:229], v[100:103]
	v_mfma_f32_16x16x32_bf16 v[96:99], v[182:185], v[226:229], v[96:99]
	s_setprio 0
	s_barrier
; #define PG8_STAGE(bufoff, gbase, voff) do { _Pragma("unroll") for (int _i = 0; _i < 2; ++_i) \
;         __builtin_amdgcn_global_load_lds((const unsigned*)((const char*)(gbase) + (voff)[_i]), (PG8_LAS unsigned*)(lds + (bufoff) + ldsw + _i * 8192), 16, 0, 0); } while (0)
; #define PG8_LDA(dst, b, h) do { _Pragma("unroll") for (int m = 0; m < 4; ++m) _Pragma("unroll") for (int k = 0; k < 2; ++k) dst[m][k] = *(const PG8_LAS bf16x8*)(lds + PG8_SA(b, h) + aoff + m * 2048 + k * 1024); } while (0)
; #define PG8_MMA(ai, bj, At, Bt) do { __builtin_amdgcn_s_setprio(1); _Pragma("unroll") for (int m = 0; m < 4; ++m) _Pragma("unroll") for (int n = 0; n < 2; ++n) _Pragma("unroll") for (int k = 0; k < 2; ++k) \
;         acc[ai][bj][m][n] = __builtin_amdgcn_mfma_f32_16x16x32_bf16(Bt[n][k], At[m][k], acc[ai][bj][m][n], 0, 0, 0); __builtin_amdgcn_s_setprio(0); } while (0)
; #define PG8_WAIT_V(n) asm volatile("s_waitcnt vmcnt(" #n ")" ::: "memory")
; #define PG8_WAIT_L(n) asm volatile("s_waitcnt lgkmcnt(" #n ")" ::: "memory")
; #define PG8_BAR __builtin_amdgcn_s_barrier()
; #define PG8_SCHED __builtin_amdgcn_sched_barrier(0)
; template <class Epi, class Sched, bool ALIGN_EPI = false, bool SP2 = false>
; __device__ __forceinline__ void gemm_phase(PG8_LAS unsigned char* lds, const Gemm g, const Sched& S, const Epi& E, int wv) {
;     ...
;         for (int t = 0; t < nt; t += 2) {
;             const bool last = (t == nt - 2);
;             const char* a1 = cA + (size_t)(t + 1) * kstep;
;             const char* a2 = last ? nA : cA + (size_t)(t + 2) * kstep; const char* b2 = last ? nB : cB + (size_t)(t + 2) * kstep;
;             const char* a3 = a2 + kstep; const char* b3 = b2 + kstep;
;     ...
;             PG8_LDA(At, 1, 1); PG8_STAGE(PG8_SB(1, 0), b3, voffB); PG8_STAGE(PG8_SB(1, 1), b3 + hstepB, voffB); PG8_STAGE(PG8_SA(1, 0), a3, voffA);
;             PG8_WAIT_V(8); PG8_WAIT_L(0); PG8_BAR; PG8_MMA(1, 0, At, B0); PG8_MMA(1, 1, At, B1); PG8_BAR; PG8_SCHED;
	s_add_i32 s0, s0, s70
	v_lshl_add_u64 v[196:197], v[196:197], 0, s[54:55]
	s_mov_b32 m0, s0
	ds_read_b128 v[186:189], v204 offset:49152
	ds_read_b128 v[190:193], v204 offset:50176
	ds_read_b128 v[206:209], v204 offset:51200
	ds_read_b128 v[210:213], v204 offset:52224
	ds_read_b128 v[214:217], v204 offset:53248
	ds_read_b128 v[218:221], v204 offset:54272
	ds_read_b128 v[222:225], v204 offset:55296
	ds_read_b128 v[226:229], v204 offset:56320
	global_load_lds_dwordx4 v[196:197], off
	v_lshl_add_u64 v[196:197], v[230:231], 0, s[54:55]
	s_add_i32 m0, s0, 0x2000
	s_add_i32 s0, s94, s70
	global_load_lds_dwordx4 v[196:197], off
	v_lshl_add_u64 v[196:197], v[232:233], 0, s[54:55]
	s_mov_b32 m0, s0
	s_nop 0
	global_load_lds_dwordx4 v[196:197], off
	v_lshl_add_u64 v[196:197], v[234:235], 0, s[54:55]
	s_add_i32 m0, s0, 0x2000
	s_nop 0
	global_load_lds_dwordx4 v[196:197], off
	v_lshl_add_u64 v[196:197], v[236:237], 0, s[54:55]
	s_mov_b32 m0, s75
	s_nop 0
	global_load_lds_dwordx4 v[196:197], off
	v_lshl_add_u64 v[196:197], v[238:239], 0, s[54:55]
	s_mov_b32 m0, s76
	s_nop 0
	global_load_lds_dwordx4 v[196:197], off
	s_waitcnt vmcnt(8)
	s_waitcnt lgkmcnt(0)
	s_barrier
	s_setprio 1
	v_mfma_f32_16x16x32_bf16 v[28:31], v[128:131], v[186:189], v[28:31]
	v_mfma_f32_16x16x32_bf16 v[24:27], v[136:139], v[186:189], v[24:27]
	v_mfma_f32_16x16x32_bf16 v[20:23], v[128:131], v[206:209], v[20:23]
	v_mfma_f32_16x16x32_bf16 v[16:19], v[136:139], v[206:209], v[16:19]
	v_mfma_f32_16x16x32_bf16 v[12:15], v[128:131], v[214:217], v[12:15]
	v_mfma_f32_16x16x32_bf16 v[8:11], v[136:139], v[214:217], v[8:11]
	v_mfma_f32_16x16x32_bf16 v[4:7], v[128:131], v[222:225], v[4:7]
	v_mfma_f32_16x16x32_bf16 v[0:3], v[136:139], v[222:225], v[0:3]
	v_mfma_f32_16x16x32_bf16 v[28:31], v[132:135], v[190:193], v[28:31]
	v_mfma_f32_16x16x32_bf16 v[24:27], v[140:143], v[190:193], v[24:27]
	v_mfma_f32_16x16x32_bf16 v[20:23], v[132:135], v[210:213], v[20:23]
	v_mfma_f32_16x16x32_bf16 v[16:19], v[140:143], v[210:213], v[16:19]
	v_mfma_f32_16x16x32_bf16 v[12:15], v[132:135], v[218:221], v[12:15]
	v_mfma_f32_16x16x32_bf16 v[8:11], v[140:143], v[218:221], v[8:11]
	v_mfma_f32_16x16x32_bf16 v[4:7], v[132:135], v[226:229], v[4:7]
	v_mfma_f32_16x16x32_bf16 v[0:3], v[140:143], v[226:229], v[0:3]
	v_mfma_f32_16x16x32_bf16 v[92:95], v[144:147], v[186:189], v[92:95]
	v_mfma_f32_16x16x32_bf16 v[88:91], v[178:181], v[186:189], v[88:91]
	v_mfma_f32_16x16x32_bf16 v[84:87], v[144:147], v[206:209], v[84:87]
	v_mfma_f32_16x16x32_bf16 v[80:83], v[178:181], v[206:209], v[80:83]
	v_mfma_f32_16x16x32_bf16 v[76:79], v[144:147], v[214:217], v[76:79]
	v_mfma_f32_16x16x32_bf16 v[72:75], v[178:181], v[214:217], v[72:75]
	v_mfma_f32_16x16x32_bf16 v[68:71], v[144:147], v[222:225], v[68:71]
	v_mfma_f32_16x16x32_bf16 v[64:67], v[178:181], v[222:225], v[64:67]
	v_mfma_f32_16x16x32_bf16 v[92:95], v[148:151], v[190:193], v[92:95]
	v_mfma_f32_16x16x32_bf16 v[88:91], v[182:185], v[190:193], v[88:91]
	v_mfma_f32_16x16x32_bf16 v[84:87], v[148:151], v[210:213], v[84:87]
	v_mfma_f32_16x16x32_bf16 v[80:83], v[182:185], v[210:213], v[80:83]
	v_mfma_f32_16x16x32_bf16 v[76:79], v[148:151], v[218:221], v[76:79]
	v_mfma_f32_16x16x32_bf16 v[72:75], v[182:185], v[218:221], v[72:75]
	v_mfma_f32_16x16x32_bf16 v[68:71], v[148:151], v[226:229], v[68:71]
	v_mfma_f32_16x16x32_bf16 v[64:67], v[182:185], v[226:229], v[64:67]
	s_setprio 0
	s_add_u32 s8, s8, 0x100
	s_addc_u32 s9, s9, 0
	s_add_u32 s64, s64, 0x100
	s_addc_u32 s65, s65, 0
	s_cmp_ge_i32 s1, s77
	s_mov_b32 s0, s1
	s_barrier
	s_cbranch_scc0 .LBB0_1874

; #define PG8_STAGE(bufoff, gbase, voff) do { _Pragma("unroll") for (int _i = 0; _i < 2; ++_i) \
;         __builtin_amdgcn_global_load_lds((const unsigned*)((const char*)(gbase) + (voff)[_i]), (PG8_LAS unsigned*)(lds + (bufoff) + ldsw + _i * 8192), 16, 0, 0); } while (0)
; #define PG8_LDA(dst, b, h) do { _Pragma("unroll") for (int m = 0; m < 4; ++m) _Pragma("unroll") for (int k = 0; k < 2; ++k) dst[m][k] = *(const PG8_LAS bf16x8*)(lds + PG8_SA(b, h) + aoff + m * 2048 + k * 1024); } while (0)
; #define PG8_LDB(dst, b, h) do { _Pragma("unroll") for (int n = 0; n < 2; ++n) _Pragma("unroll") for (int k = 0; k < 2; ++k) dst[n][k] = *(const PG8_LAS bf16x8*)(lds + PG8_SB(b, h) + boff + n * 2048 + k * 1024); } while (0)
; #define PG8_MMA(ai, bj, At, Bt) do { __builtin_amdgcn_s_setprio(1); _Pragma("unroll") for (int m = 0; m < 4; ++m) _Pragma("unroll") for (int n = 0; n < 2; ++n) _Pragma("unroll") for (int k = 0; k < 2; ++k) \
;         acc[ai][bj][m][n] = __builtin_amdgcn_mfma_f32_16x16x32_bf16(Bt[n][k], At[m][k], acc[ai][bj][m][n], 0, 0, 0); __builtin_amdgcn_s_setprio(0); } while (0)
; #define PG8_WAIT_V(n) asm volatile("s_waitcnt vmcnt(" #n ")" ::: "memory")
; #define PG8_BAR __builtin_amdgcn_s_barrier()
; template <class Epi, class Sched, bool ALIGN_EPI = false, bool SP2 = false>
; __device__ __forceinline__ void gemm_phase(PG8_LAS unsigned char* lds, const Gemm g, const Sched& S, const Epi& E, int wv) {
;     ...
;         for (int t = 0; t < nt; t += 2) {
;             const bool last = (t == nt - 2);
;             const char* a1 = cA + (size_t)(t + 1) * kstep;
;             const char* a2 = last ? nA : cA + (size_t)(t + 2) * kstep; const char* b2 = last ? nB : cB + (size_t)(t + 2) * kstep;
;             const char* a3 = a2 + kstep; const char* b3 = b2 + kstep;
;             if (last && has_next) S.a_ready(nxt);
;             if constexpr (SP2) {
;             PG8_LDB(B0, 0, 0); PG8_LDB(B1, 0, 1); PG8_SCHED; PG8_LDA(At, 0, 0); PG8_STAGE(PG8_SA(1, 1), a1 + hstepA, voffA);
;             PG8_WAIT_V(8); PG8_WAIT_L(0); PG8_BAR; PG8_MMA(0, 0, At, B0); PG8_MMA(0, 1, At, B1); PG8_BAR; PG8_SCHED;
;             PG8_LDA(At, 0, 1); PG8_STAGE(PG8_SB(0, 0), b2, voffB); PG8_STAGE(PG8_SB(0, 1), b2 + hstepB, voffB); PG8_STAGE(PG8_SA(0, 0), a2, voffA);
;             PG8_WAIT_V(8); PG8_WAIT_L(0); PG8_BAR; PG8_MMA(1, 0, At, B0); PG8_MMA(1, 1, At, B1); PG8_BAR; PG8_SCHED;
.LBB0_2016:
	ds_read_b128 v[144:147], v153
	ds_read_b128 v[156:159], v153 offset:1024
	ds_read_b128 v[160:163], v153 offset:2048
	ds_read_b128 v[164:167], v153 offset:3072
	ds_read_b128 v[168:171], v154
	ds_read_b128 v[172:175], v154 offset:1024
	ds_read_b128 v[176:179], v154 offset:2048
	ds_read_b128 v[180:183], v154 offset:3072
	s_add_u32 s0, s38, 0xfffc0080
	s_addc_u32 s1, s39, -1
	s_cmp_eq_u32 s62, 12
	s_cselect_b32 s43, s23, s1
	s_cselect_b32 s42, s29, s0
	s_cselect_b32 s41, s21, s59
	s_cselect_b32 s40, s57, s58
	s_add_i32 m0, s37, 0xc000
	ds_read_b128 v[184:187], v155
	ds_read_b128 v[188:191], v155 offset:1024
	ds_read_b128 v[192:195], v155 offset:2048
	ds_read_b128 v[196:199], v155 offset:3072
	ds_read_b128 v[200:203], v155 offset:4096
	ds_read_b128 v[204:207], v155 offset:5120
	ds_read_b128 v[208:211], v155 offset:6144
	ds_read_b128 v[212:215], v155 offset:7168
	global_load_lds_dwordx4 v136, s[38:39]
	s_add_i32 m0, s37, 0xe000
	s_nop 0
	global_load_lds_dwordx4 v138, s[38:39]
	s_waitcnt vmcnt(8)
	s_waitcnt lgkmcnt(0)
	s_barrier
	s_setprio 1
	v_mfma_f32_16x16x32_bf16 v[124:127], v[144:147], v[184:187], v[124:127]
	v_mfma_f32_16x16x32_bf16 v[120:123], v[160:163], v[184:187], v[120:123]
	v_mfma_f32_16x16x32_bf16 v[108:111], v[144:147], v[192:195], v[108:111]
	v_mfma_f32_16x16x32_bf16 v[104:107], v[160:163], v[192:195], v[104:107]
	v_mfma_f32_16x16x32_bf16 v[92:95], v[144:147], v[200:203], v[92:95]
	v_mfma_f32_16x16x32_bf16 v[88:91], v[160:163], v[200:203], v[88:91]
	v_mfma_f32_16x16x32_bf16 v[76:79], v[144:147], v[208:211], v[76:79]
	v_mfma_f32_16x16x32_bf16 v[72:75], v[160:163], v[208:211], v[72:75]
	v_mfma_f32_16x16x32_bf16 v[124:127], v[156:159], v[188:191], v[124:127]
	v_mfma_f32_16x16x32_bf16 v[120:123], v[164:167], v[188:191], v[120:123]
	v_mfma_f32_16x16x32_bf16 v[108:111], v[156:159], v[196:199], v[108:111]
	v_mfma_f32_16x16x32_bf16 v[104:107], v[164:167], v[196:199], v[104:107]
	v_mfma_f32_16x16x32_bf16 v[92:95], v[156:159], v[204:207], v[92:95]
	v_mfma_f32_16x16x32_bf16 v[88:91], v[164:167], v[204:207], v[88:91]
	v_mfma_f32_16x16x32_bf16 v[76:79], v[156:159], v[212:215], v[76:79]
	v_mfma_f32_16x16x32_bf16 v[72:75], v[164:167], v[212:215], v[72:75]
	v_mfma_f32_16x16x32_bf16 v[116:119], v[168:171], v[184:187], v[116:119]
	v_mfma_f32_16x16x32_bf16 v[112:115], v[176:179], v[184:187], v[112:115]
	v_mfma_f32_16x16x32_bf16 v[100:103], v[168:171], v[192:195], v[100:103]
	v_mfma_f32_16x16x32_bf16 v[96:99], v[176:179], v[192:195], v[96:99]
	v_mfma_f32_16x16x32_bf16 v[84:87], v[168:171], v[200:203], v[84:87]
	v_mfma_f32_16x16x32_bf16 v[80:83], v[176:179], v[200:203], v[80:83]
	v_mfma_f32_16x16x32_bf16 v[68:71], v[168:171], v[208:211], v[68:71]
	v_mfma_f32_16x16x32_bf16 v[64:67], v[176:179], v[208:211], v[64:67]
	v_mfma_f32_16x16x32_bf16 v[116:119], v[172:175], v[188:191], v[116:119]
	v_mfma_f32_16x16x32_bf16 v[112:115], v[180:183], v[188:191], v[112:115]
	v_mfma_f32_16x16x32_bf16 v[100:103], v[172:175], v[196:199], v[100:103]
	v_mfma_f32_16x16x32_bf16 v[96:99], v[180:183], v[196:199], v[96:99]
	v_mfma_f32_16x16x32_bf16 v[84:87], v[172:175], v[204:207], v[84:87]
	v_mfma_f32_16x16x32_bf16 v[80:83], v[180:183], v[204:207], v[80:83]
	v_mfma_f32_16x16x32_bf16 v[68:71], v[172:175], v[212:215], v[68:71]
	v_mfma_f32_16x16x32_bf16 v[64:67], v[180:183], v[212:215], v[64:67]
	s_setprio 0
	s_barrier
	s_add_i32 s0, s55, s46
	s_mov_b32 m0, s0
	ds_read_b128 v[184:187], v155 offset:16384
	ds_read_b128 v[188:191], v155 offset:17408
	ds_read_b128 v[192:195], v155 offset:18432
	ds_read_b128 v[196:199], v155 offset:19456
	ds_read_b128 v[200:203], v155 offset:20480
	ds_read_b128 v[204:207], v155 offset:21504
	ds_read_b128 v[208:211], v155 offset:22528
	ds_read_b128 v[212:215], v155 offset:23552
	global_load_lds_dwordx4 v130, s[40:41]
	s_add_i32 m0, s0, 0x2000
	s_add_u32 s0, s40, 0x40000
	s_addc_u32 s1, s41, 0
	s_add_i32 s63, s56, s46
	global_load_lds_dwordx4 v134, s[40:41]
	s_mov_b32 m0, s63
	s_nop 0
	global_load_lds_dwordx4 v130, s[0:1]
	s_add_i32 m0, s63, 0x2000
	s_nop 0
	global_load_lds_dwordx4 v134, s[0:1]
	s_mov_b32 m0, s37
	s_nop 0
	global_load_lds_dwordx4 v128, s[42:43]
	s_mov_b32 m0, s47
	s_nop 0
	global_load_lds_dwordx4 v132, s[42:43]
	s_waitcnt vmcnt(8)
	s_waitcnt lgkmcnt(0)
	s_barrier
	s_setprio 1
	v_mfma_f32_16x16x32_bf16 v[60:63], v[144:147], v[184:187], v[60:63]
	v_mfma_f32_16x16x32_bf16 v[56:59], v[160:163], v[184:187], v[56:59]
	v_mfma_f32_16x16x32_bf16 v[44:47], v[144:147], v[192:195], v[44:47]
	v_mfma_f32_16x16x32_bf16 v[40:43], v[160:163], v[192:195], v[40:43]
	v_mfma_f32_16x16x32_bf16 v[28:31], v[144:147], v[200:203], v[28:31]
	v_mfma_f32_16x16x32_bf16 v[24:27], v[160:163], v[200:203], v[24:27]
	v_mfma_f32_16x16x32_bf16 v[12:15], v[144:147], v[208:211], v[12:15]
	v_mfma_f32_16x16x32_bf16 v[8:11], v[160:163], v[208:211], v[8:11]
	v_mfma_f32_16x16x32_bf16 v[60:63], v[156:159], v[188:191], v[60:63]
	v_mfma_f32_16x16x32_bf16 v[56:59], v[164:167], v[188:191], v[56:59]
	v_mfma_f32_16x16x32_bf16 v[44:47], v[156:159], v[196:199], v[44:47]
	v_mfma_f32_16x16x32_bf16 v[40:43], v[164:167], v[196:199], v[40:43]
	v_mfma_f32_16x16x32_bf16 v[28:31], v[156:159], v[204:207], v[28:31]
	v_mfma_f32_16x16x32_bf16 v[24:27], v[164:167], v[204:207], v[24:27]
	v_mfma_f32_16x16x32_bf16 v[12:15], v[156:159], v[212:215], v[12:15]
	v_mfma_f32_16x16x32_bf16 v[8:11], v[164:167], v[212:215], v[8:11]
	v_mfma_f32_16x16x32_bf16 v[52:55], v[168:171], v[184:187], v[52:55]
	v_mfma_f32_16x16x32_bf16 v[48:51], v[176:179], v[184:187], v[48:51]
	v_mfma_f32_16x16x32_bf16 v[36:39], v[168:171], v[192:195], v[36:39]
	v_mfma_f32_16x16x32_bf16 v[32:35], v[176:179], v[192:195], v[32:35]
	v_mfma_f32_16x16x32_bf16 v[20:23], v[168:171], v[200:203], v[20:23]
	v_mfma_f32_16x16x32_bf16 v[16:19], v[176:179], v[200:203], v[16:19]
	v_mfma_f32_16x16x32_bf16 v[4:7], v[168:171], v[208:211], v[4:7]
	v_mfma_f32_16x16x32_bf16 v[0:3], v[176:179], v[208:211], v[0:3]
	v_mfma_f32_16x16x32_bf16 v[52:55], v[172:175], v[188:191], v[52:55]
	v_mfma_f32_16x16x32_bf16 v[48:51], v[180:183], v[188:191], v[48:51]
	v_mfma_f32_16x16x32_bf16 v[36:39], v[172:175], v[196:199], v[36:39]
	v_mfma_f32_16x16x32_bf16 v[32:35], v[180:183], v[196:199], v[32:35]
	v_mfma_f32_16x16x32_bf16 v[20:23], v[172:175], v[204:207], v[20:23]
	v_mfma_f32_16x16x32_bf16 v[16:19], v[180:183], v[204:207], v[16:19]
	v_mfma_f32_16x16x32_bf16 v[4:7], v[172:175], v[212:215], v[4:7]
	v_mfma_f32_16x16x32_bf16 v[0:3], v[180:183], v[212:215], v[0:3]
	s_setprio 0
	s_barrier
; #define PG8_STAGE(bufoff, gbase, voff) do { _Pragma("unroll") for (int _i = 0; _i < 2; ++_i) \
;         __builtin_amdgcn_global_load_lds((const unsigned*)((const char*)(gbase) + (voff)[_i]), (PG8_LAS unsigned*)(lds + (bufoff) + ldsw + _i * 8192), 16, 0, 0); } while (0)
; #define PG8_LDA(dst, b, h) do { _Pragma("unroll") for (int m = 0; m < 4; ++m) _Pragma("unroll") for (int k = 0; k < 2; ++k) dst[m][k] = *(const PG8_LAS bf16x8*)(lds + PG8_SA(b, h) + aoff + m * 2048 + k * 1024); } while (0)
; #define PG8_LDB(dst, b, h) do { _Pragma("unroll") for (int n = 0; n < 2; ++n) _Pragma("unroll") for (int k = 0; k < 2; ++k) dst[n][k] = *(const PG8_LAS bf16x8*)(lds + PG8_SB(b, h) + boff + n * 2048 + k * 1024); } while (0)
; #define PG8_MMA(ai, bj, At, Bt) do { __builtin_amdgcn_s_setprio(1); _Pragma("unroll") for (int m = 0; m < 4; ++m) _Pragma("unroll") for (int n = 0; n < 2; ++n) _Pragma("unroll") for (int k = 0; k < 2; ++k) \
;         acc[ai][bj][m][n] = __builtin_amdgcn_mfma_f32_16x16x32_bf16(Bt[n][k], At[m][k], acc[ai][bj][m][n], 0, 0, 0); __builtin_amdgcn_s_setprio(0); } while (0)
; #define PG8_WAIT_V(n) asm volatile("s_waitcnt vmcnt(" #n ")" ::: "memory")
; #define PG8_WAIT_L(n) asm volatile("s_waitcnt lgkmcnt(" #n ")" ::: "memory")
; #define PG8_BAR __builtin_amdgcn_s_barrier()
; template <class Epi, class Sched, bool ALIGN_EPI = false, bool SP2 = false>
; __device__ __forceinline__ void gemm_phase(PG8_LAS unsigned char* lds, const Gemm g, const Sched& S, const Epi& E, int wv) {
;     ...
;         for (int t = 0; t < nt; t += 2) {
;             const bool last = (t == nt - 2);
;             const char* a1 = cA + (size_t)(t + 1) * kstep;
;             const char* a2 = last ? nA : cA + (size_t)(t + 2) * kstep; const char* b2 = last ? nB : cB + (size_t)(t + 2) * kstep;
;             const char* a3 = a2 + kstep; const char* b3 = b2 + kstep;
;     ...
;             PG8_LDB(B0, 1, 0); PG8_LDB(B1, 1, 1); PG8_SCHED; PG8_LDA(At, 1, 0); PG8_STAGE(PG8_SA(0, 1), a2 + hstepA, voffA);
;             PG8_WAIT_V(8); PG8_WAIT_L(0); PG8_BAR; PG8_MMA(0, 0, At, B0); PG8_MMA(0, 1, At, B1); PG8_BAR; PG8_SCHED;
;             PG8_LDA(At, 1, 1); PG8_STAGE(PG8_SB(1, 0), b3, voffB); PG8_STAGE(PG8_SB(1, 1), b3 + hstepB, voffB); PG8_STAGE(PG8_SA(1, 0), a3, voffA);
;             PG8_WAIT_V(8); PG8_WAIT_L(0); PG8_BAR; PG8_MMA(1, 0, At, B0); PG8_MMA(1, 1, At, B1); PG8_BAR; PG8_SCHED;
	s_add_i32 s63, 0, 0x18000
	s_add_i32 s64, 0, 0x1c000
	v_add_u32_e32 v164, s63, v149
	v_add_u32_e32 v180, s64, v149
	ds_read_b128 v[144:147], v164
	ds_read_b128 v[156:159], v164 offset:1024
	ds_read_b128 v[160:163], v164 offset:2048
	ds_read_b128 v[164:167], v164 offset:3072
	ds_read_b128 v[168:171], v180
	ds_read_b128 v[172:175], v180 offset:1024
	ds_read_b128 v[176:179], v180 offset:2048
	ds_read_b128 v[180:183], v180 offset:3072
	s_add_u32 s0, s42, 0x40000
	s_addc_u32 s1, s43, 0
	s_mov_b32 m0, s48
	ds_read_b128 v[184:187], v155 offset:32768
	ds_read_b128 v[188:191], v155 offset:33792
	ds_read_b128 v[192:195], v155 offset:34816
	ds_read_b128 v[196:199], v155 offset:35840
	ds_read_b128 v[200:203], v155 offset:36864
	ds_read_b128 v[204:207], v155 offset:37888
	ds_read_b128 v[208:211], v155 offset:38912
	ds_read_b128 v[212:215], v155 offset:39936
	global_load_lds_dwordx4 v128, s[0:1]
	s_mov_b32 m0, s49
	s_nop 0
	global_load_lds_dwordx4 v132, s[0:1]
	s_waitcnt vmcnt(8)
	s_waitcnt lgkmcnt(0)
	s_barrier
	s_setprio 1
	v_mfma_f32_16x16x32_bf16 v[124:127], v[144:147], v[184:187], v[124:127]
	v_mfma_f32_16x16x32_bf16 v[120:123], v[160:163], v[184:187], v[120:123]
	v_mfma_f32_16x16x32_bf16 v[108:111], v[144:147], v[192:195], v[108:111]
	v_mfma_f32_16x16x32_bf16 v[104:107], v[160:163], v[192:195], v[104:107]
	v_mfma_f32_16x16x32_bf16 v[92:95], v[144:147], v[200:203], v[92:95]
	v_mfma_f32_16x16x32_bf16 v[88:91], v[160:163], v[200:203], v[88:91]
	v_mfma_f32_16x16x32_bf16 v[76:79], v[144:147], v[208:211], v[76:79]
	v_mfma_f32_16x16x32_bf16 v[72:75], v[160:163], v[208:211], v[72:75]
	v_mfma_f32_16x16x32_bf16 v[124:127], v[156:159], v[188:191], v[124:127]
	v_mfma_f32_16x16x32_bf16 v[120:123], v[164:167], v[188:191], v[120:123]
	v_mfma_f32_16x16x32_bf16 v[108:111], v[156:159], v[196:199], v[108:111]
	v_mfma_f32_16x16x32_bf16 v[104:107], v[164:167], v[196:199], v[104:107]
	v_mfma_f32_16x16x32_bf16 v[92:95], v[156:159], v[204:207], v[92:95]
	v_mfma_f32_16x16x32_bf16 v[88:91], v[164:167], v[204:207], v[88:91]
	v_mfma_f32_16x16x32_bf16 v[76:79], v[156:159], v[212:215], v[76:79]
	v_mfma_f32_16x16x32_bf16 v[72:75], v[164:167], v[212:215], v[72:75]
	v_mfma_f32_16x16x32_bf16 v[116:119], v[168:171], v[184:187], v[116:119]
	v_mfma_f32_16x16x32_bf16 v[112:115], v[176:179], v[184:187], v[112:115]
	v_mfma_f32_16x16x32_bf16 v[100:103], v[168:171], v[192:195], v[100:103]
	v_mfma_f32_16x16x32_bf16 v[96:99], v[176:179], v[192:195], v[96:99]
	v_mfma_f32_16x16x32_bf16 v[84:87], v[168:171], v[200:203], v[84:87]
	v_mfma_f32_16x16x32_bf16 v[80:83], v[176:179], v[200:203], v[80:83]
	v_mfma_f32_16x16x32_bf16 v[68:71], v[168:171], v[208:211], v[68:71]
	v_mfma_f32_16x16x32_bf16 v[64:67], v[176:179], v[208:211], v[64:67]
	v_mfma_f32_16x16x32_bf16 v[116:119], v[172:175], v[188:191], v[116:119]
	v_mfma_f32_16x16x32_bf16 v[112:115], v[180:183], v[188:191], v[112:115]
	v_mfma_f32_16x16x32_bf16 v[100:103], v[172:175], v[196:199], v[100:103]
	v_mfma_f32_16x16x32_bf16 v[96:99], v[180:183], v[196:199], v[96:99]
	v_mfma_f32_16x16x32_bf16 v[84:87], v[172:175], v[204:207], v[84:87]
	v_mfma_f32_16x16x32_bf16 v[80:83], v[180:183], v[204:207], v[80:83]
	v_mfma_f32_16x16x32_bf16 v[68:71], v[172:175], v[212:215], v[68:71]
	v_mfma_f32_16x16x32_bf16 v[64:67], v[180:183], v[212:215], v[64:67]
	s_setprio 0
	s_barrier
	s_add_i32 s0, s63, s46
	s_add_u32 s76, s40, 0x80
	s_addc_u32 s77, s41, 0
	s_mov_b32 m0, s0
	ds_read_b128 v[184:187], v155 offset:49152
	ds_read_b128 v[188:191], v155 offset:50176
	ds_read_b128 v[192:195], v155 offset:51200
	ds_read_b128 v[196:199], v155 offset:52224
	ds_read_b128 v[200:203], v155 offset:53248
	ds_read_b128 v[204:207], v155 offset:54272
	ds_read_b128 v[208:211], v155 offset:55296
	ds_read_b128 v[212:215], v155 offset:56320
	global_load_lds_dwordx4 v130, s[76:77]
	s_add_i32 m0, s0, 0x2000
	s_add_u32 s0, s40, 0x40080
	s_addc_u32 s1, s41, 0
	s_add_i32 s40, s64, s46
	global_load_lds_dwordx4 v134, s[76:77]
	s_mov_b32 m0, s40
	s_nop 0
	global_load_lds_dwordx4 v130, s[0:1]
	s_add_i32 m0, s40, 0x2000
	s_nop 0
	global_load_lds_dwordx4 v134, s[0:1]
	s_add_u32 s78, s42, 0x80
	s_addc_u32 s79, s43, 0
	s_mov_b32 m0, s51
	s_nop 0
	global_load_lds_dwordx4 v128, s[78:79]
	s_mov_b32 m0, s52
	s_nop 0
	global_load_lds_dwordx4 v132, s[78:79]
	s_waitcnt vmcnt(8)
	s_waitcnt lgkmcnt(0)
	s_barrier
	s_setprio 1
	v_mfma_f32_16x16x32_bf16 v[60:63], v[144:147], v[184:187], v[60:63]
	v_mfma_f32_16x16x32_bf16 v[56:59], v[160:163], v[184:187], v[56:59]
	v_mfma_f32_16x16x32_bf16 v[44:47], v[144:147], v[192:195], v[44:47]
	v_mfma_f32_16x16x32_bf16 v[40:43], v[160:163], v[192:195], v[40:43]
	v_mfma_f32_16x16x32_bf16 v[28:31], v[144:147], v[200:203], v[28:31]
	v_mfma_f32_16x16x32_bf16 v[24:27], v[160:163], v[200:203], v[24:27]
	v_mfma_f32_16x16x32_bf16 v[12:15], v[144:147], v[208:211], v[12:15]
	v_mfma_f32_16x16x32_bf16 v[8:11], v[160:163], v[208:211], v[8:11]
	v_mfma_f32_16x16x32_bf16 v[60:63], v[156:159], v[188:191], v[60:63]
	v_mfma_f32_16x16x32_bf16 v[56:59], v[164:167], v[188:191], v[56:59]
	v_mfma_f32_16x16x32_bf16 v[44:47], v[156:159], v[196:199], v[44:47]
	v_mfma_f32_16x16x32_bf16 v[40:43], v[164:167], v[196:199], v[40:43]
	v_mfma_f32_16x16x32_bf16 v[28:31], v[156:159], v[204:207], v[28:31]
	v_mfma_f32_16x16x32_bf16 v[24:27], v[164:167], v[204:207], v[24:27]
	v_mfma_f32_16x16x32_bf16 v[12:15], v[156:159], v[212:215], v[12:15]
	v_mfma_f32_16x16x32_bf16 v[8:11], v[164:167], v[212:215], v[8:11]
	v_mfma_f32_16x16x32_bf16 v[52:55], v[168:171], v[184:187], v[52:55]
	v_mfma_f32_16x16x32_bf16 v[48:51], v[176:179], v[184:187], v[48:51]
	v_mfma_f32_16x16x32_bf16 v[36:39], v[168:171], v[192:195], v[36:39]
	v_mfma_f32_16x16x32_bf16 v[32:35], v[176:179], v[192:195], v[32:35]
	v_mfma_f32_16x16x32_bf16 v[20:23], v[168:171], v[200:203], v[20:23]
	v_mfma_f32_16x16x32_bf16 v[16:19], v[176:179], v[200:203], v[16:19]
	v_mfma_f32_16x16x32_bf16 v[4:7], v[168:171], v[208:211], v[4:7]
	v_mfma_f32_16x16x32_bf16 v[0:3], v[176:179], v[208:211], v[0:3]
	v_mfma_f32_16x16x32_bf16 v[52:55], v[172:175], v[188:191], v[52:55]
	v_mfma_f32_16x16x32_bf16 v[48:51], v[180:183], v[188:191], v[48:51]
	v_mfma_f32_16x16x32_bf16 v[36:39], v[172:175], v[196:199], v[36:39]
	v_mfma_f32_16x16x32_bf16 v[32:35], v[180:183], v[196:199], v[32:35]
	v_mfma_f32_16x16x32_bf16 v[20:23], v[172:175], v[204:207], v[20:23]
	v_mfma_f32_16x16x32_bf16 v[16:19], v[180:183], v[204:207], v[16:19]
	v_mfma_f32_16x16x32_bf16 v[4:7], v[172:175], v[212:215], v[4:7]
	v_mfma_f32_16x16x32_bf16 v[0:3], v[180:183], v[212:215], v[0:3]
	s_setprio 0
	s_add_i32 s62, s62, 2
	s_add_u32 s38, s38, 0x100
	s_addc_u32 s39, s39, 0
	s_add_u32 s58, s58, 0x100
	s_addc_u32 s59, s59, 0
	s_cmp_gt_u32 s62, 13
	s_barrier
	s_cbranch_scc0 .LBB0_2016
	s_and_b64 vcc, exec, s[18:19]
	s_cbranch_vccz .LBB0_2019
	s_barrier

; #define PG8_STAGE(bufoff, gbase, voff) do { _Pragma("unroll") for (int _i = 0; _i < 2; ++_i) \
;         __builtin_amdgcn_global_load_lds((const unsigned*)((const char*)(gbase) + (voff)[_i]), (PG8_LAS unsigned*)(lds + (bufoff) + ldsw + _i * 8192), 16, 0, 0); } while (0)
; #define PG8_LDA(dst, b, h) do { _Pragma("unroll") for (int m = 0; m < 4; ++m) _Pragma("unroll") for (int k = 0; k < 2; ++k) dst[m][k] = *(const PG8_LAS bf16x8*)(lds + PG8_SA(b, h) + aoff + m * 2048 + k * 1024); } while (0)
; #define PG8_LDB(dst, b, h) do { _Pragma("unroll") for (int n = 0; n < 2; ++n) _Pragma("unroll") for (int k = 0; k < 2; ++k) dst[n][k] = *(const PG8_LAS bf16x8*)(lds + PG8_SB(b, h) + boff + n * 2048 + k * 1024); } while (0)
; #define PG8_WAIT_V(n) asm volatile("s_waitcnt vmcnt(" #n ")" ::: "memory")
; #define PG8_WAIT_L(n) asm volatile("s_waitcnt lgkmcnt(" #n ")" ::: "memory")
; #define PG8_BAR __builtin_amdgcn_s_barrier()
; template <class Epi, class Sched, bool ALIGN_EPI = false, bool SP2 = false>
; __device__ __forceinline__ void gemm_phase(PG8_LAS unsigned char* lds, const Gemm g, const Sched& S, const Epi& E, int wv) {
;     ...
;         const bool has_next = S.next(ui + 1, nxt);
;         const char* nA = has_next ? (const char*)g.A + (size_t)nxt.pm * tstepA : cA; const char* nB = has_next ? (const char*)g.Bt + (size_t)nxt.pn * tstepB : cB;
;         for (int t = 0; t < nt; t += 2) {
;             const bool last = (t == nt - 2);
;             const char* a1 = cA + (size_t)(t + 1) * kstep;
;             const char* a2 = last ? nA : cA + (size_t)(t + 2) * kstep; const char* b2 = last ? nB : cB + (size_t)(t + 2) * kstep;
;             const char* a3 = a2 + kstep; const char* b3 = b2 + kstep;
;             if (last && has_next) S.a_ready(nxt);
;             if constexpr (SP2) {
;             PG8_LDB(B0, 0, 0); PG8_LDB(B1, 0, 1); PG8_SCHED; PG8_LDA(At, 0, 0); PG8_STAGE(PG8_SA(1, 1), a1 + hstepA, voffA);
;             PG8_WAIT_V(8); PG8_WAIT_L(0); PG8_BAR; PG8_MMA(0, 0, At, B0); PG8_MMA(0, 1, At, B1); PG8_BAR; PG8_SCHED;
;     ...
; #pragma unroll
;         for (int a = 0; a < 2; ++a)
; #pragma unroll
;             for (int b = 0; b < 2; ++b)
; #pragma unroll
;                 for (int m = 0; m < 4; ++m)
; #pragma unroll
;                     for (int n = 0; n < 2; ++n) acc[a][b][m][n] = (f32x4){0.f, 0.f, 0.f, 0.f};
;         cur = nxt; cA = nA; cB = nB; ++ui;
.LBB0_2066:
	s_ashr_i32 s37, s36, 31
	s_lshl_b64 s[0:1], s[36:37], 19
	s_add_u32 s38, s34, s0
	s_addc_u32 s39, s35, s1
	s_and_b64 s[0:1], s[4:5], exec
	s_cselect_b32 s37, s39, s43
	s_cselect_b32 s67, s38, s42
	s_ashr_i32 s29, s28, 31
	s_lshl_b64 s[0:1], s[28:29], 19
	s_add_u32 s40, s49, s0
	s_addc_u32 s41, s50, s1
	s_and_b64 s[0:1], s[4:5], exec
	s_cselect_b32 s29, s41, s45
	s_cselect_b32 s68, s40, s44
	s_add_u32 s42, s42, 0x40080
	s_addc_u32 s43, s43, 0
	s_add_u32 s69, s44, 0x100
	v_mov_b32_e32 v0, 0
	s_addc_u32 s70, s45, 0
	s_mov_b32 s71, -2
	v_mov_b32_e32 v1, v0
	v_mov_b32_e32 v2, v0
	v_mov_b32_e32 v3, v0
	v_mov_b32_e32 v4, v0
	v_mov_b32_e32 v5, v0
	v_mov_b32_e32 v6, v0
	v_mov_b32_e32 v7, v0
	v_mov_b32_e32 v16, v0
	v_mov_b32_e32 v17, v0
	v_mov_b32_e32 v18, v0
	v_mov_b32_e32 v19, v0
	v_mov_b32_e32 v20, v0
	v_mov_b32_e32 v21, v0
	v_mov_b32_e32 v22, v0
	v_mov_b32_e32 v23, v0
	v_mov_b32_e32 v32, v0
	v_mov_b32_e32 v33, v0
	v_mov_b32_e32 v34, v0
	v_mov_b32_e32 v35, v0
	v_mov_b32_e32 v36, v0
	v_mov_b32_e32 v37, v0
	v_mov_b32_e32 v38, v0
	v_mov_b32_e32 v39, v0
	v_mov_b32_e32 v48, v0
	v_mov_b32_e32 v49, v0
	v_mov_b32_e32 v50, v0
	v_mov_b32_e32 v51, v0
	v_mov_b32_e32 v52, v0
	v_mov_b32_e32 v53, v0
	v_mov_b32_e32 v54, v0
	v_mov_b32_e32 v55, v0
	v_mov_b32_e32 v8, v0
	v_mov_b32_e32 v9, v0
	v_mov_b32_e32 v10, v0
	v_mov_b32_e32 v11, v0
	v_mov_b32_e32 v12, v0
	v_mov_b32_e32 v13, v0
	v_mov_b32_e32 v14, v0
	v_mov_b32_e32 v15, v0
	v_mov_b32_e32 v24, v0
	v_mov_b32_e32 v25, v0
	v_mov_b32_e32 v26, v0
	v_mov_b32_e32 v27, v0
	v_mov_b32_e32 v28, v0
	v_mov_b32_e32 v29, v0
	v_mov_b32_e32 v30, v0
	v_mov_b32_e32 v31, v0
	v_mov_b32_e32 v40, v0
	v_mov_b32_e32 v41, v0
	v_mov_b32_e32 v42, v0
	v_mov_b32_e32 v43, v0
	v_mov_b32_e32 v44, v0
	v_mov_b32_e32 v45, v0
	v_mov_b32_e32 v46, v0
	v_mov_b32_e32 v47, v0
	v_mov_b32_e32 v56, v0
	v_mov_b32_e32 v57, v0
	v_mov_b32_e32 v58, v0
	v_mov_b32_e32 v59, v0
	v_mov_b32_e32 v60, v0
	v_mov_b32_e32 v61, v0
	v_mov_b32_e32 v62, v0
	v_mov_b32_e32 v63, v0
	v_mov_b32_e32 v64, v0
	v_mov_b32_e32 v65, v0
	v_mov_b32_e32 v66, v0
	v_mov_b32_e32 v67, v0
	v_mov_b32_e32 v68, v0
	v_mov_b32_e32 v69, v0
	v_mov_b32_e32 v70, v0
	v_mov_b32_e32 v71, v0
	v_mov_b32_e32 v80, v0
	v_mov_b32_e32 v81, v0
	v_mov_b32_e32 v82, v0
	v_mov_b32_e32 v83, v0
	v_mov_b32_e32 v84, v0
	v_mov_b32_e32 v85, v0
	v_mov_b32_e32 v86, v0
	v_mov_b32_e32 v87, v0
	v_mov_b32_e32 v96, v0
	v_mov_b32_e32 v97, v0
	v_mov_b32_e32 v98, v0
	v_mov_b32_e32 v99, v0
	v_mov_b32_e32 v100, v0
	v_mov_b32_e32 v101, v0
	v_mov_b32_e32 v102, v0
	v_mov_b32_e32 v103, v0
	v_mov_b32_e32 v112, v0
	v_mov_b32_e32 v113, v0
	v_mov_b32_e32 v114, v0
	v_mov_b32_e32 v115, v0
	v_mov_b32_e32 v116, v0
	v_mov_b32_e32 v117, v0
	v_mov_b32_e32 v118, v0
	v_mov_b32_e32 v119, v0
	v_mov_b32_e32 v72, v0
	v_mov_b32_e32 v73, v0
	v_mov_b32_e32 v74, v0
	v_mov_b32_e32 v75, v0
	v_mov_b32_e32 v76, v0
	v_mov_b32_e32 v77, v0
	v_mov_b32_e32 v78, v0
	v_mov_b32_e32 v79, v0
	v_mov_b32_e32 v88, v0
	v_mov_b32_e32 v89, v0
	v_mov_b32_e32 v90, v0
	v_mov_b32_e32 v91, v0
	v_mov_b32_e32 v92, v0
	v_mov_b32_e32 v93, v0
	v_mov_b32_e32 v94, v0
	v_mov_b32_e32 v95, v0
	v_mov_b32_e32 v104, v0
	v_mov_b32_e32 v105, v0
	v_mov_b32_e32 v106, v0
	v_mov_b32_e32 v107, v0
	v_mov_b32_e32 v108, v0
	v_mov_b32_e32 v109, v0
	v_mov_b32_e32 v110, v0
	v_mov_b32_e32 v111, v0
	v_mov_b32_e32 v120, v0
	v_mov_b32_e32 v121, v0
	v_mov_b32_e32 v122, v0
	v_mov_b32_e32 v123, v0
	v_mov_b32_e32 v124, v0
	v_mov_b32_e32 v125, v0
	v_mov_b32_e32 v126, v0
	v_mov_b32_e32 v127, v0
	v_add_u32_e32 v216, 0x18000, v153
	v_add_u32_e32 v217, 0x1c000, v153
.LBB0_2067:
	ds_read_b128 v[144:147], v155
	ds_read_b128 v[148:151], v155 offset:1024
	ds_read_b128 v[160:163], v155 offset:2048
	ds_read_b128 v[164:167], v155 offset:3072
	ds_read_b128 v[168:171], v156
	ds_read_b128 v[172:175], v156 offset:1024
	ds_read_b128 v[176:179], v156 offset:2048
	ds_read_b128 v[180:183], v156 offset:3072
	s_add_u32 s0, s42, 0xfffc0080
	s_addc_u32 s1, s43, -1
	s_cmp_eq_u32 s71, 12
	s_cselect_b32 s47, s37, s1
	s_cselect_b32 s46, s67, s0
	s_cselect_b32 s45, s29, s70
	s_cselect_b32 s44, s68, s69
	s_add_i32 m0, s52, 0xc000
	ds_read_b128 v[184:187], v157
	ds_read_b128 v[188:191], v157 offset:1024
	ds_read_b128 v[192:195], v157 offset:2048
	ds_read_b128 v[196:199], v157 offset:3072
	ds_read_b128 v[200:203], v157 offset:4096
	ds_read_b128 v[204:207], v157 offset:5120
	ds_read_b128 v[208:211], v157 offset:6144
	ds_read_b128 v[212:215], v157 offset:7168
	global_load_lds_dwordx4 v136, s[42:43]
	s_add_i32 m0, s52, 0xe000
	s_nop 0
	global_load_lds_dwordx4 v138, s[42:43]
	s_waitcnt vmcnt(8)
	s_waitcnt lgkmcnt(0)
	s_barrier
; #define PG8_STAGE(bufoff, gbase, voff) do { _Pragma("unroll") for (int _i = 0; _i < 2; ++_i) \
;         __builtin_amdgcn_global_load_lds((const unsigned*)((const char*)(gbase) + (voff)[_i]), (PG8_LAS unsigned*)(lds + (bufoff) + ldsw + _i * 8192), 16, 0, 0); } while (0)
; #define PG8_LDA(dst, b, h) do { _Pragma("unroll") for (int m = 0; m < 4; ++m) _Pragma("unroll") for (int k = 0; k < 2; ++k) dst[m][k] = *(const PG8_LAS bf16x8*)(lds + PG8_SA(b, h) + aoff + m * 2048 + k * 1024); } while (0)
; #define PG8_MMA(ai, bj, At, Bt) do { __builtin_amdgcn_s_setprio(1); _Pragma("unroll") for (int m = 0; m < 4; ++m) _Pragma("unroll") for (int n = 0; n < 2; ++n) _Pragma("unroll") for (int k = 0; k < 2; ++k) \
;         acc[ai][bj][m][n] = __builtin_amdgcn_mfma_f32_16x16x32_bf16(Bt[n][k], At[m][k], acc[ai][bj][m][n], 0, 0, 0); __builtin_amdgcn_s_setprio(0); } while (0)
; #define PG8_WAIT_V(n) asm volatile("s_waitcnt vmcnt(" #n ")" ::: "memory")
; #define PG8_WAIT_L(n) asm volatile("s_waitcnt lgkmcnt(" #n ")" ::: "memory")
; #define PG8_BAR __builtin_amdgcn_s_barrier()
; #define PG8_SCHED __builtin_amdgcn_sched_barrier(0)
; template <class Epi, class Sched, bool ALIGN_EPI = false, bool SP2 = false>
; __device__ __forceinline__ void gemm_phase(PG8_LAS unsigned char* lds, const Gemm g, const Sched& S, const Epi& E, int wv) {
;     ...
;             PG8_WAIT_V(8); PG8_WAIT_L(0); PG8_BAR; PG8_MMA(0, 0, At, B0); PG8_MMA(0, 1, At, B1); PG8_BAR; PG8_SCHED;
;             PG8_LDA(At, 0, 1); PG8_STAGE(PG8_SB(0, 0), b2, voffB); PG8_STAGE(PG8_SB(0, 1), b2 + hstepB, voffB); PG8_STAGE(PG8_SA(0, 0), a2, voffA);
;             PG8_WAIT_V(8); PG8_WAIT_L(0); PG8_BAR; PG8_MMA(1, 0, At, B0); PG8_MMA(1, 1, At, B1); PG8_BAR; PG8_SCHED;
	s_setprio 1
	v_mfma_f32_16x16x32_bf16 v[124:127], v[144:147], v[184:187], v[124:127]
	v_mfma_f32_16x16x32_bf16 v[120:123], v[160:163], v[184:187], v[120:123]
	v_mfma_f32_16x16x32_bf16 v[108:111], v[144:147], v[192:195], v[108:111]
	v_mfma_f32_16x16x32_bf16 v[104:107], v[160:163], v[192:195], v[104:107]
	v_mfma_f32_16x16x32_bf16 v[92:95], v[144:147], v[200:203], v[92:95]
	v_mfma_f32_16x16x32_bf16 v[88:91], v[160:163], v[200:203], v[88:91]
	v_mfma_f32_16x16x32_bf16 v[76:79], v[144:147], v[208:211], v[76:79]
	v_mfma_f32_16x16x32_bf16 v[72:75], v[160:163], v[208:211], v[72:75]
	v_mfma_f32_16x16x32_bf16 v[124:127], v[148:151], v[188:191], v[124:127]
	v_mfma_f32_16x16x32_bf16 v[120:123], v[164:167], v[188:191], v[120:123]
	v_mfma_f32_16x16x32_bf16 v[108:111], v[148:151], v[196:199], v[108:111]
	v_mfma_f32_16x16x32_bf16 v[104:107], v[164:167], v[196:199], v[104:107]
	v_mfma_f32_16x16x32_bf16 v[92:95], v[148:151], v[204:207], v[92:95]
	v_mfma_f32_16x16x32_bf16 v[88:91], v[164:167], v[204:207], v[88:91]
	v_mfma_f32_16x16x32_bf16 v[76:79], v[148:151], v[212:215], v[76:79]
	v_mfma_f32_16x16x32_bf16 v[72:75], v[164:167], v[212:215], v[72:75]
	v_mfma_f32_16x16x32_bf16 v[116:119], v[168:171], v[184:187], v[116:119]
	v_mfma_f32_16x16x32_bf16 v[112:115], v[176:179], v[184:187], v[112:115]
	v_mfma_f32_16x16x32_bf16 v[100:103], v[168:171], v[192:195], v[100:103]
	v_mfma_f32_16x16x32_bf16 v[96:99], v[176:179], v[192:195], v[96:99]
	v_mfma_f32_16x16x32_bf16 v[84:87], v[168:171], v[200:203], v[84:87]
	v_mfma_f32_16x16x32_bf16 v[80:83], v[176:179], v[200:203], v[80:83]
	v_mfma_f32_16x16x32_bf16 v[68:71], v[168:171], v[208:211], v[68:71]
	v_mfma_f32_16x16x32_bf16 v[64:67], v[176:179], v[208:211], v[64:67]
	v_mfma_f32_16x16x32_bf16 v[116:119], v[172:175], v[188:191], v[116:119]
	v_mfma_f32_16x16x32_bf16 v[112:115], v[180:183], v[188:191], v[112:115]
	v_mfma_f32_16x16x32_bf16 v[100:103], v[172:175], v[196:199], v[100:103]
	v_mfma_f32_16x16x32_bf16 v[96:99], v[180:183], v[196:199], v[96:99]
	v_mfma_f32_16x16x32_bf16 v[84:87], v[172:175], v[204:207], v[84:87]
	v_mfma_f32_16x16x32_bf16 v[80:83], v[180:183], v[204:207], v[80:83]
	v_mfma_f32_16x16x32_bf16 v[68:71], v[172:175], v[212:215], v[68:71]
	v_mfma_f32_16x16x32_bf16 v[64:67], v[180:183], v[212:215], v[64:67]
	s_setprio 0
	s_barrier
	s_add_i32 s0, s60, s51
	s_mov_b32 m0, s0
	ds_read_b128 v[184:187], v157 offset:16384
	ds_read_b128 v[188:191], v157 offset:17408
	ds_read_b128 v[192:195], v157 offset:18432
	ds_read_b128 v[196:199], v157 offset:19456
	ds_read_b128 v[200:203], v157 offset:20480
	ds_read_b128 v[204:207], v157 offset:21504
	ds_read_b128 v[208:211], v157 offset:22528
	ds_read_b128 v[212:215], v157 offset:23552
	global_load_lds_dwordx4 v130, s[44:45]
	s_add_i32 m0, s0, 0x2000
	s_add_u32 s0, s44, 0x40000
	s_addc_u32 s1, s45, 0
	s_add_i32 s72, s61, s51
	global_load_lds_dwordx4 v134, s[44:45]
	s_mov_b32 m0, s72
	s_nop 0
	global_load_lds_dwordx4 v130, s[0:1]
	s_add_i32 m0, s72, 0x2000
	s_nop 0
	global_load_lds_dwordx4 v134, s[0:1]
	s_mov_b32 m0, s52
	s_nop 0
	global_load_lds_dwordx4 v128, s[46:47]
	s_mov_b32 m0, s53
	s_nop 0
	global_load_lds_dwordx4 v132, s[46:47]
	s_waitcnt vmcnt(8)
	s_waitcnt lgkmcnt(0)
	s_barrier
	s_setprio 1
	v_mfma_f32_16x16x32_bf16 v[60:63], v[144:147], v[184:187], v[60:63]
	v_mfma_f32_16x16x32_bf16 v[56:59], v[160:163], v[184:187], v[56:59]
	v_mfma_f32_16x16x32_bf16 v[44:47], v[144:147], v[192:195], v[44:47]
	v_mfma_f32_16x16x32_bf16 v[40:43], v[160:163], v[192:195], v[40:43]
	v_mfma_f32_16x16x32_bf16 v[28:31], v[144:147], v[200:203], v[28:31]
	v_mfma_f32_16x16x32_bf16 v[24:27], v[160:163], v[200:203], v[24:27]
	v_mfma_f32_16x16x32_bf16 v[12:15], v[144:147], v[208:211], v[12:15]
	v_mfma_f32_16x16x32_bf16 v[8:11], v[160:163], v[208:211], v[8:11]
	v_mfma_f32_16x16x32_bf16 v[60:63], v[148:151], v[188:191], v[60:63]
	v_mfma_f32_16x16x32_bf16 v[56:59], v[164:167], v[188:191], v[56:59]
	v_mfma_f32_16x16x32_bf16 v[44:47], v[148:151], v[196:199], v[44:47]
	v_mfma_f32_16x16x32_bf16 v[40:43], v[164:167], v[196:199], v[40:43]
	v_mfma_f32_16x16x32_bf16 v[28:31], v[148:151], v[204:207], v[28:31]
	v_mfma_f32_16x16x32_bf16 v[24:27], v[164:167], v[204:207], v[24:27]
	v_mfma_f32_16x16x32_bf16 v[12:15], v[148:151], v[212:215], v[12:15]
	v_mfma_f32_16x16x32_bf16 v[8:11], v[164:167], v[212:215], v[8:11]
	v_mfma_f32_16x16x32_bf16 v[52:55], v[168:171], v[184:187], v[52:55]
	v_mfma_f32_16x16x32_bf16 v[48:51], v[176:179], v[184:187], v[48:51]
	v_mfma_f32_16x16x32_bf16 v[36:39], v[168:171], v[192:195], v[36:39]
	v_mfma_f32_16x16x32_bf16 v[32:35], v[176:179], v[192:195], v[32:35]
	v_mfma_f32_16x16x32_bf16 v[20:23], v[168:171], v[200:203], v[20:23]
	v_mfma_f32_16x16x32_bf16 v[16:19], v[176:179], v[200:203], v[16:19]
	v_mfma_f32_16x16x32_bf16 v[4:7], v[168:171], v[208:211], v[4:7]
	v_mfma_f32_16x16x32_bf16 v[0:3], v[176:179], v[208:211], v[0:3]
	v_mfma_f32_16x16x32_bf16 v[52:55], v[172:175], v[188:191], v[52:55]
	v_mfma_f32_16x16x32_bf16 v[48:51], v[180:183], v[188:191], v[48:51]
	v_mfma_f32_16x16x32_bf16 v[36:39], v[172:175], v[196:199], v[36:39]
	v_mfma_f32_16x16x32_bf16 v[32:35], v[180:183], v[196:199], v[32:35]
	v_mfma_f32_16x16x32_bf16 v[20:23], v[172:175], v[204:207], v[20:23]
	v_mfma_f32_16x16x32_bf16 v[16:19], v[180:183], v[204:207], v[16:19]
	v_mfma_f32_16x16x32_bf16 v[4:7], v[172:175], v[212:215], v[4:7]
	v_mfma_f32_16x16x32_bf16 v[0:3], v[180:183], v[212:215], v[0:3]
	s_setprio 0
	s_barrier
; #define PG8_STAGE(bufoff, gbase, voff) do { _Pragma("unroll") for (int _i = 0; _i < 2; ++_i) \
;         __builtin_amdgcn_global_load_lds((const unsigned*)((const char*)(gbase) + (voff)[_i]), (PG8_LAS unsigned*)(lds + (bufoff) + ldsw + _i * 8192), 16, 0, 0); } while (0)
; #define PG8_LDA(dst, b, h) do { _Pragma("unroll") for (int m = 0; m < 4; ++m) _Pragma("unroll") for (int k = 0; k < 2; ++k) dst[m][k] = *(const PG8_LAS bf16x8*)(lds + PG8_SA(b, h) + aoff + m * 2048 + k * 1024); } while (0)
; #define PG8_LDB(dst, b, h) do { _Pragma("unroll") for (int n = 0; n < 2; ++n) _Pragma("unroll") for (int k = 0; k < 2; ++k) dst[n][k] = *(const PG8_LAS bf16x8*)(lds + PG8_SB(b, h) + boff + n * 2048 + k * 1024); } while (0)
; #define PG8_MMA(ai, bj, At, Bt) do { __builtin_amdgcn_s_setprio(1); _Pragma("unroll") for (int m = 0; m < 4; ++m) _Pragma("unroll") for (int n = 0; n < 2; ++n) _Pragma("unroll") for (int k = 0; k < 2; ++k) \
;         acc[ai][bj][m][n] = __builtin_amdgcn_mfma_f32_16x16x32_bf16(Bt[n][k], At[m][k], acc[ai][bj][m][n], 0, 0, 0); __builtin_amdgcn_s_setprio(0); } while (0)
; #define PG8_WAIT_V(n) asm volatile("s_waitcnt vmcnt(" #n ")" ::: "memory")
; #define PG8_WAIT_L(n) asm volatile("s_waitcnt lgkmcnt(" #n ")" ::: "memory")
; #define PG8_BAR __builtin_amdgcn_s_barrier()
; template <class Epi, class Sched, bool ALIGN_EPI = false, bool SP2 = false>
; __device__ __forceinline__ void gemm_phase(PG8_LAS unsigned char* lds, const Gemm g, const Sched& S, const Epi& E, int wv) {
;     ...
;         for (int t = 0; t < nt; t += 2) {
;             const bool last = (t == nt - 2);
;             const char* a1 = cA + (size_t)(t + 1) * kstep;
;             const char* a2 = last ? nA : cA + (size_t)(t + 2) * kstep; const char* b2 = last ? nB : cB + (size_t)(t + 2) * kstep;
;             const char* a3 = a2 + kstep; const char* b3 = b2 + kstep;
;     ...
;             PG8_LDB(B0, 1, 0); PG8_LDB(B1, 1, 1); PG8_SCHED; PG8_LDA(At, 1, 0); PG8_STAGE(PG8_SA(0, 1), a2 + hstepA, voffA);
;             PG8_WAIT_V(8); PG8_WAIT_L(0); PG8_BAR; PG8_MMA(0, 0, At, B0); PG8_MMA(0, 1, At, B1); PG8_BAR; PG8_SCHED;
;             PG8_LDA(At, 1, 1); PG8_STAGE(PG8_SB(1, 0), b3, voffB); PG8_STAGE(PG8_SB(1, 1), b3 + hstepB, voffB); PG8_STAGE(PG8_SA(1, 0), a3, voffA);
;             PG8_WAIT_V(8); PG8_WAIT_L(0); PG8_BAR; PG8_MMA(1, 0, At, B0); PG8_MMA(1, 1, At, B1); PG8_BAR; PG8_SCHED;
	s_add_i32 s72, 0, 0x18000
	s_add_i32 s73, 0, 0x1c000
	ds_read_b128 v[144:147], v216
	ds_read_b128 v[148:151], v216 offset:1024
	ds_read_b128 v[160:163], v216 offset:2048
	ds_read_b128 v[164:167], v216 offset:3072
	ds_read_b128 v[168:171], v217
	ds_read_b128 v[172:175], v217 offset:1024
	ds_read_b128 v[176:179], v217 offset:2048
	ds_read_b128 v[180:183], v217 offset:3072
	s_add_u32 s0, s46, 0x40000
	s_addc_u32 s1, s47, 0
	s_mov_b32 m0, s54
	ds_read_b128 v[184:187], v157 offset:32768
	ds_read_b128 v[188:191], v157 offset:33792
	ds_read_b128 v[192:195], v157 offset:34816
	ds_read_b128 v[196:199], v157 offset:35840
	ds_read_b128 v[200:203], v157 offset:36864
	ds_read_b128 v[204:207], v157 offset:37888
	ds_read_b128 v[208:211], v157 offset:38912
	ds_read_b128 v[212:215], v157 offset:39936
	global_load_lds_dwordx4 v128, s[0:1]
	s_mov_b32 m0, s55
	s_nop 0
	global_load_lds_dwordx4 v132, s[0:1]
	s_waitcnt vmcnt(8)
	s_waitcnt lgkmcnt(0)
	s_barrier
	s_setprio 1
	v_mfma_f32_16x16x32_bf16 v[124:127], v[144:147], v[184:187], v[124:127]
	v_mfma_f32_16x16x32_bf16 v[120:123], v[160:163], v[184:187], v[120:123]
	v_mfma_f32_16x16x32_bf16 v[108:111], v[144:147], v[192:195], v[108:111]
	v_mfma_f32_16x16x32_bf16 v[104:107], v[160:163], v[192:195], v[104:107]
	v_mfma_f32_16x16x32_bf16 v[92:95], v[144:147], v[200:203], v[92:95]
	v_mfma_f32_16x16x32_bf16 v[88:91], v[160:163], v[200:203], v[88:91]
	v_mfma_f32_16x16x32_bf16 v[76:79], v[144:147], v[208:211], v[76:79]
	v_mfma_f32_16x16x32_bf16 v[72:75], v[160:163], v[208:211], v[72:75]
	v_mfma_f32_16x16x32_bf16 v[124:127], v[148:151], v[188:191], v[124:127]
	v_mfma_f32_16x16x32_bf16 v[120:123], v[164:167], v[188:191], v[120:123]
	v_mfma_f32_16x16x32_bf16 v[108:111], v[148:151], v[196:199], v[108:111]
	v_mfma_f32_16x16x32_bf16 v[104:107], v[164:167], v[196:199], v[104:107]
	v_mfma_f32_16x16x32_bf16 v[92:95], v[148:151], v[204:207], v[92:95]
	v_mfma_f32_16x16x32_bf16 v[88:91], v[164:167], v[204:207], v[88:91]
	v_mfma_f32_16x16x32_bf16 v[76:79], v[148:151], v[212:215], v[76:79]
	v_mfma_f32_16x16x32_bf16 v[72:75], v[164:167], v[212:215], v[72:75]
	v_mfma_f32_16x16x32_bf16 v[116:119], v[168:171], v[184:187], v[116:119]
	v_mfma_f32_16x16x32_bf16 v[112:115], v[176:179], v[184:187], v[112:115]
	v_mfma_f32_16x16x32_bf16 v[100:103], v[168:171], v[192:195], v[100:103]
	v_mfma_f32_16x16x32_bf16 v[96:99], v[176:179], v[192:195], v[96:99]
	v_mfma_f32_16x16x32_bf16 v[84:87], v[168:171], v[200:203], v[84:87]
	v_mfma_f32_16x16x32_bf16 v[80:83], v[176:179], v[200:203], v[80:83]
	v_mfma_f32_16x16x32_bf16 v[68:71], v[168:171], v[208:211], v[68:71]
	v_mfma_f32_16x16x32_bf16 v[64:67], v[176:179], v[208:211], v[64:67]
	v_mfma_f32_16x16x32_bf16 v[116:119], v[172:175], v[188:191], v[116:119]
	v_mfma_f32_16x16x32_bf16 v[112:115], v[180:183], v[188:191], v[112:115]
	v_mfma_f32_16x16x32_bf16 v[100:103], v[172:175], v[196:199], v[100:103]
	v_mfma_f32_16x16x32_bf16 v[96:99], v[180:183], v[196:199], v[96:99]
	v_mfma_f32_16x16x32_bf16 v[84:87], v[172:175], v[204:207], v[84:87]
	v_mfma_f32_16x16x32_bf16 v[80:83], v[180:183], v[204:207], v[80:83]
	v_mfma_f32_16x16x32_bf16 v[68:71], v[172:175], v[212:215], v[68:71]
	v_mfma_f32_16x16x32_bf16 v[64:67], v[180:183], v[212:215], v[64:67]
	s_setprio 0
	s_barrier
	s_add_i32 s0, s72, s51
	s_add_u32 s76, s44, 0x80
	s_addc_u32 s77, s45, 0
	s_mov_b32 m0, s0
	ds_read_b128 v[184:187], v157 offset:49152
	ds_read_b128 v[188:191], v157 offset:50176
	ds_read_b128 v[192:195], v157 offset:51200
	ds_read_b128 v[196:199], v157 offset:52224
	ds_read_b128 v[200:203], v157 offset:53248
	ds_read_b128 v[204:207], v157 offset:54272
	ds_read_b128 v[208:211], v157 offset:55296
	ds_read_b128 v[212:215], v157 offset:56320
	global_load_lds_dwordx4 v130, s[76:77]
	s_add_i32 m0, s0, 0x2000
	s_add_u32 s0, s44, 0x40080
	s_addc_u32 s1, s45, 0
	s_add_i32 s44, s73, s51
	global_load_lds_dwordx4 v134, s[76:77]
	s_mov_b32 m0, s44
	s_nop 0
	global_load_lds_dwordx4 v130, s[0:1]
	s_add_i32 m0, s44, 0x2000
	s_nop 0
	global_load_lds_dwordx4 v134, s[0:1]
	s_add_u32 s78, s46, 0x80
	s_addc_u32 s79, s47, 0
	s_mov_b32 m0, s57
	s_nop 0
	global_load_lds_dwordx4 v128, s[78:79]
	s_mov_b32 m0, s58
	s_nop 0
	global_load_lds_dwordx4 v132, s[78:79]
	s_waitcnt vmcnt(8)
	s_waitcnt lgkmcnt(0)
	s_barrier
	s_setprio 1
	v_mfma_f32_16x16x32_bf16 v[60:63], v[144:147], v[184:187], v[60:63]
	v_mfma_f32_16x16x32_bf16 v[56:59], v[160:163], v[184:187], v[56:59]
	v_mfma_f32_16x16x32_bf16 v[44:47], v[144:147], v[192:195], v[44:47]
	v_mfma_f32_16x16x32_bf16 v[40:43], v[160:163], v[192:195], v[40:43]
	v_mfma_f32_16x16x32_bf16 v[28:31], v[144:147], v[200:203], v[28:31]
	v_mfma_f32_16x16x32_bf16 v[24:27], v[160:163], v[200:203], v[24:27]
	v_mfma_f32_16x16x32_bf16 v[12:15], v[144:147], v[208:211], v[12:15]
	v_mfma_f32_16x16x32_bf16 v[8:11], v[160:163], v[208:211], v[8:11]
	v_mfma_f32_16x16x32_bf16 v[60:63], v[148:151], v[188:191], v[60:63]
	v_mfma_f32_16x16x32_bf16 v[56:59], v[164:167], v[188:191], v[56:59]
	v_mfma_f32_16x16x32_bf16 v[44:47], v[148:151], v[196:199], v[44:47]
	v_mfma_f32_16x16x32_bf16 v[40:43], v[164:167], v[196:199], v[40:43]
	v_mfma_f32_16x16x32_bf16 v[28:31], v[148:151], v[204:207], v[28:31]
	v_mfma_f32_16x16x32_bf16 v[24:27], v[164:167], v[204:207], v[24:27]
	v_mfma_f32_16x16x32_bf16 v[12:15], v[148:151], v[212:215], v[12:15]
	v_mfma_f32_16x16x32_bf16 v[8:11], v[164:167], v[212:215], v[8:11]
	v_mfma_f32_16x16x32_bf16 v[52:55], v[168:171], v[184:187], v[52:55]
	v_mfma_f32_16x16x32_bf16 v[48:51], v[176:179], v[184:187], v[48:51]
	v_mfma_f32_16x16x32_bf16 v[36:39], v[168:171], v[192:195], v[36:39]
	v_mfma_f32_16x16x32_bf16 v[32:35], v[176:179], v[192:195], v[32:35]
	v_mfma_f32_16x16x32_bf16 v[20:23], v[168:171], v[200:203], v[20:23]
	v_mfma_f32_16x16x32_bf16 v[16:19], v[176:179], v[200:203], v[16:19]
	v_mfma_f32_16x16x32_bf16 v[4:7], v[168:171], v[208:211], v[4:7]
	v_mfma_f32_16x16x32_bf16 v[0:3], v[176:179], v[208:211], v[0:3]
	v_mfma_f32_16x16x32_bf16 v[52:55], v[172:175], v[188:191], v[52:55]
	v_mfma_f32_16x16x32_bf16 v[48:51], v[180:183], v[188:191], v[48:51]
	v_mfma_f32_16x16x32_bf16 v[36:39], v[172:175], v[196:199], v[36:39]
	v_mfma_f32_16x16x32_bf16 v[32:35], v[180:183], v[196:199], v[32:35]
	v_mfma_f32_16x16x32_bf16 v[20:23], v[172:175], v[204:207], v[20:23]
	v_mfma_f32_16x16x32_bf16 v[16:19], v[180:183], v[204:207], v[16:19]
	v_mfma_f32_16x16x32_bf16 v[4:7], v[172:175], v[212:215], v[4:7]
	v_mfma_f32_16x16x32_bf16 v[0:3], v[180:183], v[212:215], v[0:3]
	s_setprio 0
	s_add_i32 s71, s71, 2
	s_add_u32 s42, s42, 0x100
	s_addc_u32 s43, s43, 0
	s_add_u32 s69, s69, 0x100
	s_addc_u32 s70, s70, 0
	s_cmp_gt_u32 s71, 13
	s_barrier
	s_cbranch_scc0 .LBB0_2067
	s_and_b64 vcc, exec, s[18:19]
	s_cbranch_vccz .LBB0_2070
	s_barrier

; #define PG8_STAGE(bufoff, gbase, voff) do { _Pragma("unroll") for (int _i = 0; _i < 2; ++_i) \
;         __builtin_amdgcn_global_load_lds((const unsigned*)((const char*)(gbase) + (voff)[_i]), (PG8_LAS unsigned*)(lds + (bufoff) + ldsw + _i * 8192), 16, 0, 0); } while (0)
; #define PG8_LDA(dst, b, h) do { _Pragma("unroll") for (int m = 0; m < 4; ++m) _Pragma("unroll") for (int k = 0; k < 2; ++k) dst[m][k] = *(const PG8_LAS bf16x8*)(lds + PG8_SA(b, h) + aoff + m * 2048 + k * 1024); } while (0)
; #define PG8_LDB(dst, b, h) do { _Pragma("unroll") for (int n = 0; n < 2; ++n) _Pragma("unroll") for (int k = 0; k < 2; ++k) dst[n][k] = *(const PG8_LAS bf16x8*)(lds + PG8_SB(b, h) + boff + n * 2048 + k * 1024); } while (0)
; #define PG8_WAIT_V(n) asm volatile("s_waitcnt vmcnt(" #n ")" ::: "memory")
; #define PG8_WAIT_L(n) asm volatile("s_waitcnt lgkmcnt(" #n ")" ::: "memory")
; #define PG8_BAR __builtin_amdgcn_s_barrier()
; template <class Epi, class Sched, bool ALIGN_EPI = false, bool SP2 = false>
; __device__ __forceinline__ void gemm_phase(PG8_LAS unsigned char* lds, const Gemm g, const Sched& S, const Epi& E, int wv) {
;     ...
;         const bool has_next = S.next(ui + 1, nxt);
;         const char* nA = has_next ? (const char*)g.A + (size_t)nxt.pm * tstepA : cA; const char* nB = has_next ? (const char*)g.Bt + (size_t)nxt.pn * tstepB : cB;
;         for (int t = 0; t < nt; t += 2) {
;             const bool last = (t == nt - 2);
;             const char* a1 = cA + (size_t)(t + 1) * kstep;
;             const char* a2 = last ? nA : cA + (size_t)(t + 2) * kstep; const char* b2 = last ? nB : cB + (size_t)(t + 2) * kstep;
;             const char* a3 = a2 + kstep; const char* b3 = b2 + kstep;
;             if (last && has_next) S.a_ready(nxt);
;             if constexpr (SP2) {
;             PG8_LDB(B0, 0, 0); PG8_LDB(B1, 0, 1); PG8_SCHED; PG8_LDA(At, 0, 0); PG8_STAGE(PG8_SA(1, 1), a1 + hstepA, voffA);
;             PG8_WAIT_V(8); PG8_WAIT_L(0); PG8_BAR; PG8_MMA(0, 0, At, B0); PG8_MMA(0, 1, At, B1); PG8_BAR; PG8_SCHED;
;     ...
; #pragma unroll
;         for (int a = 0; a < 2; ++a)
; #pragma unroll
;             for (int b = 0; b < 2; ++b)
; #pragma unroll
;                 for (int m = 0; m < 4; ++m)
; #pragma unroll
;                     for (int n = 0; n < 2; ++n) acc[a][b][m][n] = (f32x4){0.f, 0.f, 0.f, 0.f};
;         cur = nxt; cA = nA; cB = nB; ++ui;
.LBB0_2101:
	s_ashr_i32 s23, s22, 31
	s_lshl_b64 s[24:25], s[22:23], 21
	s_add_u32 s24, s14, s24
	s_addc_u32 s25, s15, s25
	s_and_b64 s[26:27], s[0:1], exec
	s_cselect_b32 s23, s25, s37
	s_cselect_b32 s55, s24, s36
	s_ashr_i32 s21, s20, 31
	s_lshl_b64 s[26:27], s[20:21], 21
	s_add_u32 s26, s42, s26
	s_addc_u32 s27, s43, s27
	s_and_b64 s[40:41], s[0:1], exec
	s_cselect_b32 s21, s27, s39
	s_cselect_b32 s56, s26, s38
	s_add_u32 s36, s36, 0x100080
	s_addc_u32 s37, s37, 0
	s_add_u32 s57, s38, 0x100
	v_mov_b32_e32 v0, 0
	s_addc_u32 s58, s39, 0
	s_mov_b32 s59, -2
	v_mov_b32_e32 v1, v0
	v_mov_b32_e32 v2, v0
	v_mov_b32_e32 v3, v0
	v_mov_b32_e32 v4, v0
	v_mov_b32_e32 v5, v0
	v_mov_b32_e32 v6, v0
	v_mov_b32_e32 v7, v0
	v_mov_b32_e32 v16, v0
	v_mov_b32_e32 v17, v0
	v_mov_b32_e32 v18, v0
	v_mov_b32_e32 v19, v0
	v_mov_b32_e32 v20, v0
	v_mov_b32_e32 v21, v0
	v_mov_b32_e32 v22, v0
	v_mov_b32_e32 v23, v0
	v_mov_b32_e32 v32, v0
	v_mov_b32_e32 v33, v0
	v_mov_b32_e32 v34, v0
	v_mov_b32_e32 v35, v0
	v_mov_b32_e32 v36, v0
	v_mov_b32_e32 v37, v0
	v_mov_b32_e32 v38, v0
	v_mov_b32_e32 v39, v0
	v_mov_b32_e32 v48, v0
	v_mov_b32_e32 v49, v0
	v_mov_b32_e32 v50, v0
	v_mov_b32_e32 v51, v0
	v_mov_b32_e32 v52, v0
	v_mov_b32_e32 v53, v0
	v_mov_b32_e32 v54, v0
	v_mov_b32_e32 v55, v0
	v_mov_b32_e32 v8, v0
	v_mov_b32_e32 v9, v0
	v_mov_b32_e32 v10, v0
	v_mov_b32_e32 v11, v0
	v_mov_b32_e32 v12, v0
	v_mov_b32_e32 v13, v0
	v_mov_b32_e32 v14, v0
	v_mov_b32_e32 v15, v0
	v_mov_b32_e32 v24, v0
	v_mov_b32_e32 v25, v0
	v_mov_b32_e32 v26, v0
	v_mov_b32_e32 v27, v0
	v_mov_b32_e32 v28, v0
	v_mov_b32_e32 v29, v0
	v_mov_b32_e32 v30, v0
	v_mov_b32_e32 v31, v0
	v_mov_b32_e32 v40, v0
	v_mov_b32_e32 v41, v0
	v_mov_b32_e32 v42, v0
	v_mov_b32_e32 v43, v0
	v_mov_b32_e32 v44, v0
	v_mov_b32_e32 v45, v0
	v_mov_b32_e32 v46, v0
	v_mov_b32_e32 v47, v0
	v_mov_b32_e32 v56, v0
	v_mov_b32_e32 v57, v0
	v_mov_b32_e32 v58, v0
	v_mov_b32_e32 v59, v0
	v_mov_b32_e32 v60, v0
	v_mov_b32_e32 v61, v0
	v_mov_b32_e32 v62, v0
	v_mov_b32_e32 v63, v0
	v_mov_b32_e32 v64, v0
	v_mov_b32_e32 v65, v0
	v_mov_b32_e32 v66, v0
	v_mov_b32_e32 v67, v0
	v_mov_b32_e32 v68, v0
	v_mov_b32_e32 v69, v0
	v_mov_b32_e32 v70, v0
	v_mov_b32_e32 v71, v0
	v_mov_b32_e32 v80, v0
	v_mov_b32_e32 v81, v0
	v_mov_b32_e32 v82, v0
	v_mov_b32_e32 v83, v0
	v_mov_b32_e32 v84, v0
	v_mov_b32_e32 v85, v0
	v_mov_b32_e32 v86, v0
	v_mov_b32_e32 v87, v0
	v_mov_b32_e32 v96, v0
	v_mov_b32_e32 v97, v0
	v_mov_b32_e32 v98, v0
	v_mov_b32_e32 v99, v0
	v_mov_b32_e32 v100, v0
	v_mov_b32_e32 v101, v0
	v_mov_b32_e32 v102, v0
	v_mov_b32_e32 v103, v0
	v_mov_b32_e32 v112, v0
	v_mov_b32_e32 v113, v0
	v_mov_b32_e32 v114, v0
	v_mov_b32_e32 v115, v0
	v_mov_b32_e32 v116, v0
	v_mov_b32_e32 v117, v0
	v_mov_b32_e32 v118, v0
	v_mov_b32_e32 v119, v0
	v_mov_b32_e32 v72, v0
	v_mov_b32_e32 v73, v0
	v_mov_b32_e32 v74, v0
	v_mov_b32_e32 v75, v0
	v_mov_b32_e32 v76, v0
	v_mov_b32_e32 v77, v0
	v_mov_b32_e32 v78, v0
	v_mov_b32_e32 v79, v0
	v_mov_b32_e32 v88, v0
	v_mov_b32_e32 v89, v0
	v_mov_b32_e32 v90, v0
	v_mov_b32_e32 v91, v0
	v_mov_b32_e32 v92, v0
	v_mov_b32_e32 v93, v0
	v_mov_b32_e32 v94, v0
	v_mov_b32_e32 v95, v0
	v_mov_b32_e32 v104, v0
	v_mov_b32_e32 v105, v0
	v_mov_b32_e32 v106, v0
	v_mov_b32_e32 v107, v0
	v_mov_b32_e32 v108, v0
	v_mov_b32_e32 v109, v0
	v_mov_b32_e32 v110, v0
	v_mov_b32_e32 v111, v0
	v_mov_b32_e32 v120, v0
	v_mov_b32_e32 v121, v0
	v_mov_b32_e32 v122, v0
	v_mov_b32_e32 v123, v0
	v_mov_b32_e32 v124, v0
	v_mov_b32_e32 v125, v0
	v_mov_b32_e32 v126, v0
	v_mov_b32_e32 v127, v0
	v_add_u32_e32 v216, 0x18000, v151
	v_add_u32_e32 v217, 0x1c000, v151
.LBB0_2102:
	ds_read_b128 v[144:147], v153
	ds_read_b128 v[156:159], v153 offset:1024
	ds_read_b128 v[160:163], v153 offset:2048
	ds_read_b128 v[164:167], v153 offset:3072
	ds_read_b128 v[168:171], v154
	ds_read_b128 v[172:175], v154 offset:1024
	ds_read_b128 v[176:179], v154 offset:2048
	ds_read_b128 v[180:183], v154 offset:3072
	s_add_u32 s38, s36, 0xfff00080
	s_addc_u32 s39, s37, -1
	s_cmp_eq_u32 s59, 60
	s_cselect_b32 s41, s23, s39
	s_cselect_b32 s40, s55, s38
	s_cselect_b32 s39, s21, s58
	s_cselect_b32 s38, s56, s57
	s_add_i32 m0, s29, 0xc000
	ds_read_b128 v[184:187], v155
	ds_read_b128 v[188:191], v155 offset:1024
	ds_read_b128 v[192:195], v155 offset:2048
	ds_read_b128 v[196:199], v155 offset:3072
	ds_read_b128 v[200:203], v155 offset:4096
	ds_read_b128 v[204:207], v155 offset:5120
	ds_read_b128 v[208:211], v155 offset:6144
	ds_read_b128 v[212:215], v155 offset:7168
	global_load_lds_dwordx4 v136, s[36:37]
	s_add_i32 m0, s29, 0xe000
	s_nop 0
	global_load_lds_dwordx4 v138, s[36:37]
	s_waitcnt vmcnt(8)
	s_waitcnt lgkmcnt(0)
	s_barrier
; #define PG8_STAGE(bufoff, gbase, voff) do { _Pragma("unroll") for (int _i = 0; _i < 2; ++_i) \
;         __builtin_amdgcn_global_load_lds((const unsigned*)((const char*)(gbase) + (voff)[_i]), (PG8_LAS unsigned*)(lds + (bufoff) + ldsw + _i * 8192), 16, 0, 0); } while (0)
; #define PG8_LDA(dst, b, h) do { _Pragma("unroll") for (int m = 0; m < 4; ++m) _Pragma("unroll") for (int k = 0; k < 2; ++k) dst[m][k] = *(const PG8_LAS bf16x8*)(lds + PG8_SA(b, h) + aoff + m * 2048 + k * 1024); } while (0)
; #define PG8_MMA(ai, bj, At, Bt) do { __builtin_amdgcn_s_setprio(1); _Pragma("unroll") for (int m = 0; m < 4; ++m) _Pragma("unroll") for (int n = 0; n < 2; ++n) _Pragma("unroll") for (int k = 0; k < 2; ++k) \
;         acc[ai][bj][m][n] = __builtin_amdgcn_mfma_f32_16x16x32_bf16(Bt[n][k], At[m][k], acc[ai][bj][m][n], 0, 0, 0); __builtin_amdgcn_s_setprio(0); } while (0)
; #define PG8_WAIT_V(n) asm volatile("s_waitcnt vmcnt(" #n ")" ::: "memory")
; #define PG8_WAIT_L(n) asm volatile("s_waitcnt lgkmcnt(" #n ")" ::: "memory")
; #define PG8_BAR __builtin_amdgcn_s_barrier()
; #define PG8_SCHED __builtin_amdgcn_sched_barrier(0)
; template <class Epi, class Sched, bool ALIGN_EPI = false, bool SP2 = false>
; __device__ __forceinline__ void gemm_phase(PG8_LAS unsigned char* lds, const Gemm g, const Sched& S, const Epi& E, int wv) {
;     ...
;             PG8_WAIT_V(8); PG8_WAIT_L(0); PG8_BAR; PG8_MMA(0, 0, At, B0); PG8_MMA(0, 1, At, B1); PG8_BAR; PG8_SCHED;
;             PG8_LDA(At, 0, 1); PG8_STAGE(PG8_SB(0, 0), b2, voffB); PG8_STAGE(PG8_SB(0, 1), b2 + hstepB, voffB); PG8_STAGE(PG8_SA(0, 0), a2, voffA);
;             PG8_WAIT_V(8); PG8_WAIT_L(0); PG8_BAR; PG8_MMA(1, 0, At, B0); PG8_MMA(1, 1, At, B1); PG8_BAR; PG8_SCHED;
	s_setprio 1
	v_mfma_f32_16x16x32_bf16 v[124:127], v[144:147], v[184:187], v[124:127]
	v_mfma_f32_16x16x32_bf16 v[120:123], v[160:163], v[184:187], v[120:123]
	v_mfma_f32_16x16x32_bf16 v[108:111], v[144:147], v[192:195], v[108:111]
	v_mfma_f32_16x16x32_bf16 v[104:107], v[160:163], v[192:195], v[104:107]
	v_mfma_f32_16x16x32_bf16 v[92:95], v[144:147], v[200:203], v[92:95]
	v_mfma_f32_16x16x32_bf16 v[88:91], v[160:163], v[200:203], v[88:91]
	v_mfma_f32_16x16x32_bf16 v[76:79], v[144:147], v[208:211], v[76:79]
	v_mfma_f32_16x16x32_bf16 v[72:75], v[160:163], v[208:211], v[72:75]
	v_mfma_f32_16x16x32_bf16 v[124:127], v[156:159], v[188:191], v[124:127]
	v_mfma_f32_16x16x32_bf16 v[120:123], v[164:167], v[188:191], v[120:123]
	v_mfma_f32_16x16x32_bf16 v[108:111], v[156:159], v[196:199], v[108:111]
	v_mfma_f32_16x16x32_bf16 v[104:107], v[164:167], v[196:199], v[104:107]
	v_mfma_f32_16x16x32_bf16 v[92:95], v[156:159], v[204:207], v[92:95]
	v_mfma_f32_16x16x32_bf16 v[88:91], v[164:167], v[204:207], v[88:91]
	v_mfma_f32_16x16x32_bf16 v[76:79], v[156:159], v[212:215], v[76:79]
	v_mfma_f32_16x16x32_bf16 v[72:75], v[164:167], v[212:215], v[72:75]
	v_mfma_f32_16x16x32_bf16 v[116:119], v[168:171], v[184:187], v[116:119]
	v_mfma_f32_16x16x32_bf16 v[112:115], v[176:179], v[184:187], v[112:115]
	v_mfma_f32_16x16x32_bf16 v[100:103], v[168:171], v[192:195], v[100:103]
	v_mfma_f32_16x16x32_bf16 v[96:99], v[176:179], v[192:195], v[96:99]
	v_mfma_f32_16x16x32_bf16 v[84:87], v[168:171], v[200:203], v[84:87]
	v_mfma_f32_16x16x32_bf16 v[80:83], v[176:179], v[200:203], v[80:83]
	v_mfma_f32_16x16x32_bf16 v[68:71], v[168:171], v[208:211], v[68:71]
	v_mfma_f32_16x16x32_bf16 v[64:67], v[176:179], v[208:211], v[64:67]
	v_mfma_f32_16x16x32_bf16 v[116:119], v[172:175], v[188:191], v[116:119]
	v_mfma_f32_16x16x32_bf16 v[112:115], v[180:183], v[188:191], v[112:115]
	v_mfma_f32_16x16x32_bf16 v[100:103], v[172:175], v[196:199], v[100:103]
	v_mfma_f32_16x16x32_bf16 v[96:99], v[180:183], v[196:199], v[96:99]
	v_mfma_f32_16x16x32_bf16 v[84:87], v[172:175], v[204:207], v[84:87]
	v_mfma_f32_16x16x32_bf16 v[80:83], v[180:183], v[204:207], v[80:83]
	v_mfma_f32_16x16x32_bf16 v[68:71], v[172:175], v[212:215], v[68:71]
	v_mfma_f32_16x16x32_bf16 v[64:67], v[180:183], v[212:215], v[64:67]
	s_setprio 0
	s_barrier
	s_add_i32 s60, s52, s44
	s_mov_b32 m0, s60
	ds_read_b128 v[184:187], v155 offset:16384
	ds_read_b128 v[188:191], v155 offset:17408
	ds_read_b128 v[192:195], v155 offset:18432
	ds_read_b128 v[196:199], v155 offset:19456
	ds_read_b128 v[200:203], v155 offset:20480
	ds_read_b128 v[204:207], v155 offset:21504
	ds_read_b128 v[208:211], v155 offset:22528
	ds_read_b128 v[212:215], v155 offset:23552
	global_load_lds_dwordx4 v130, s[38:39]
	s_add_i32 m0, s60, 0x2000
	s_add_u32 s60, s38, 0x100000
	s_addc_u32 s61, s39, 0
	s_add_i32 s62, s53, s44
	global_load_lds_dwordx4 v134, s[38:39]
	s_mov_b32 m0, s62
	s_add_u32 s82, s40, 0x80
	s_addc_u32 s83, s41, 0
	global_load_lds_dwordx4 v130, s[60:61]
	s_add_i32 m0, s62, 0x2000
	s_nop 0
	global_load_lds_dwordx4 v134, s[60:61]
	s_mov_b32 m0, s29
	s_nop 0
	global_load_lds_dwordx4 v128, s[40:41]
	s_mov_b32 m0, s45
	s_nop 0
	global_load_lds_dwordx4 v132, s[40:41]
	s_waitcnt vmcnt(8)
	s_waitcnt lgkmcnt(0)
	s_barrier
	s_setprio 1
	v_mfma_f32_16x16x32_bf16 v[60:63], v[144:147], v[184:187], v[60:63]
	v_mfma_f32_16x16x32_bf16 v[56:59], v[160:163], v[184:187], v[56:59]
	v_mfma_f32_16x16x32_bf16 v[44:47], v[144:147], v[192:195], v[44:47]
	v_mfma_f32_16x16x32_bf16 v[40:43], v[160:163], v[192:195], v[40:43]
	v_mfma_f32_16x16x32_bf16 v[28:31], v[144:147], v[200:203], v[28:31]
	v_mfma_f32_16x16x32_bf16 v[24:27], v[160:163], v[200:203], v[24:27]
	v_mfma_f32_16x16x32_bf16 v[12:15], v[144:147], v[208:211], v[12:15]
	v_mfma_f32_16x16x32_bf16 v[8:11], v[160:163], v[208:211], v[8:11]
	v_mfma_f32_16x16x32_bf16 v[60:63], v[156:159], v[188:191], v[60:63]
	v_mfma_f32_16x16x32_bf16 v[56:59], v[164:167], v[188:191], v[56:59]
	v_mfma_f32_16x16x32_bf16 v[44:47], v[156:159], v[196:199], v[44:47]
	v_mfma_f32_16x16x32_bf16 v[40:43], v[164:167], v[196:199], v[40:43]
	v_mfma_f32_16x16x32_bf16 v[28:31], v[156:159], v[204:207], v[28:31]
	v_mfma_f32_16x16x32_bf16 v[24:27], v[164:167], v[204:207], v[24:27]
	v_mfma_f32_16x16x32_bf16 v[12:15], v[156:159], v[212:215], v[12:15]
	v_mfma_f32_16x16x32_bf16 v[8:11], v[164:167], v[212:215], v[8:11]
	v_mfma_f32_16x16x32_bf16 v[52:55], v[168:171], v[184:187], v[52:55]
	v_mfma_f32_16x16x32_bf16 v[48:51], v[176:179], v[184:187], v[48:51]
	v_mfma_f32_16x16x32_bf16 v[36:39], v[168:171], v[192:195], v[36:39]
	v_mfma_f32_16x16x32_bf16 v[32:35], v[176:179], v[192:195], v[32:35]
	v_mfma_f32_16x16x32_bf16 v[20:23], v[168:171], v[200:203], v[20:23]
	v_mfma_f32_16x16x32_bf16 v[16:19], v[176:179], v[200:203], v[16:19]
	v_mfma_f32_16x16x32_bf16 v[4:7], v[168:171], v[208:211], v[4:7]
	v_mfma_f32_16x16x32_bf16 v[0:3], v[176:179], v[208:211], v[0:3]
	v_mfma_f32_16x16x32_bf16 v[52:55], v[172:175], v[188:191], v[52:55]
	v_mfma_f32_16x16x32_bf16 v[48:51], v[180:183], v[188:191], v[48:51]
	v_mfma_f32_16x16x32_bf16 v[36:39], v[172:175], v[196:199], v[36:39]
	v_mfma_f32_16x16x32_bf16 v[32:35], v[180:183], v[196:199], v[32:35]
	v_mfma_f32_16x16x32_bf16 v[20:23], v[172:175], v[204:207], v[20:23]
	v_mfma_f32_16x16x32_bf16 v[16:19], v[180:183], v[204:207], v[16:19]
	v_mfma_f32_16x16x32_bf16 v[4:7], v[172:175], v[212:215], v[4:7]
	v_mfma_f32_16x16x32_bf16 v[0:3], v[180:183], v[212:215], v[0:3]
	s_setprio 0
	s_barrier
; #define PG8_STAGE(bufoff, gbase, voff) do { _Pragma("unroll") for (int _i = 0; _i < 2; ++_i) \
;         __builtin_amdgcn_global_load_lds((const unsigned*)((const char*)(gbase) + (voff)[_i]), (PG8_LAS unsigned*)(lds + (bufoff) + ldsw + _i * 8192), 16, 0, 0); } while (0)
; #define PG8_LDA(dst, b, h) do { _Pragma("unroll") for (int m = 0; m < 4; ++m) _Pragma("unroll") for (int k = 0; k < 2; ++k) dst[m][k] = *(const PG8_LAS bf16x8*)(lds + PG8_SA(b, h) + aoff + m * 2048 + k * 1024); } while (0)
; #define PG8_LDB(dst, b, h) do { _Pragma("unroll") for (int n = 0; n < 2; ++n) _Pragma("unroll") for (int k = 0; k < 2; ++k) dst[n][k] = *(const PG8_LAS bf16x8*)(lds + PG8_SB(b, h) + boff + n * 2048 + k * 1024); } while (0)
; #define PG8_MMA(ai, bj, At, Bt) do { __builtin_amdgcn_s_setprio(1); _Pragma("unroll") for (int m = 0; m < 4; ++m) _Pragma("unroll") for (int n = 0; n < 2; ++n) _Pragma("unroll") for (int k = 0; k < 2; ++k) \
;         acc[ai][bj][m][n] = __builtin_amdgcn_mfma_f32_16x16x32_bf16(Bt[n][k], At[m][k], acc[ai][bj][m][n], 0, 0, 0); __builtin_amdgcn_s_setprio(0); } while (0)
; #define PG8_WAIT_V(n) asm volatile("s_waitcnt vmcnt(" #n ")" ::: "memory")
; #define PG8_WAIT_L(n) asm volatile("s_waitcnt lgkmcnt(" #n ")" ::: "memory")
; #define PG8_BAR __builtin_amdgcn_s_barrier()
; template <class Epi, class Sched, bool ALIGN_EPI = false, bool SP2 = false>
; __device__ __forceinline__ void gemm_phase(PG8_LAS unsigned char* lds, const Gemm g, const Sched& S, const Epi& E, int wv) {
;     ...
;         for (int t = 0; t < nt; t += 2) {
;             const bool last = (t == nt - 2);
;             const char* a1 = cA + (size_t)(t + 1) * kstep;
;             const char* a2 = last ? nA : cA + (size_t)(t + 2) * kstep; const char* b2 = last ? nB : cB + (size_t)(t + 2) * kstep;
;             const char* a3 = a2 + kstep; const char* b3 = b2 + kstep;
;     ...
;             PG8_LDB(B0, 1, 0); PG8_LDB(B1, 1, 1); PG8_SCHED; PG8_LDA(At, 1, 0); PG8_STAGE(PG8_SA(0, 1), a2 + hstepA, voffA);
;             PG8_WAIT_V(8); PG8_WAIT_L(0); PG8_BAR; PG8_MMA(0, 0, At, B0); PG8_MMA(0, 1, At, B1); PG8_BAR; PG8_SCHED;
;             PG8_LDA(At, 1, 1); PG8_STAGE(PG8_SB(1, 0), b3, voffB); PG8_STAGE(PG8_SB(1, 1), b3 + hstepB, voffB); PG8_STAGE(PG8_SA(1, 0), a3, voffA);
;             PG8_WAIT_V(8); PG8_WAIT_L(0); PG8_BAR; PG8_MMA(1, 0, At, B0); PG8_MMA(1, 1, At, B1); PG8_BAR; PG8_SCHED;
	s_add_i32 s60, 0, 0x18000
	s_add_i32 s61, 0, 0x1c000
	ds_read_b128 v[144:147], v216
	ds_read_b128 v[156:159], v216 offset:1024
	ds_read_b128 v[160:163], v216 offset:2048
	ds_read_b128 v[164:167], v216 offset:3072
	ds_read_b128 v[168:171], v217
	ds_read_b128 v[172:175], v217 offset:1024
	ds_read_b128 v[176:179], v217 offset:2048
	ds_read_b128 v[180:183], v217 offset:3072
	s_add_u32 s40, s40, 0x100000
	s_addc_u32 s41, s41, 0
	s_mov_b32 m0, s46
	ds_read_b128 v[184:187], v155 offset:32768
	ds_read_b128 v[188:191], v155 offset:33792
	ds_read_b128 v[192:195], v155 offset:34816
	ds_read_b128 v[196:199], v155 offset:35840
	ds_read_b128 v[200:203], v155 offset:36864
	ds_read_b128 v[204:207], v155 offset:37888
	ds_read_b128 v[208:211], v155 offset:38912
	ds_read_b128 v[212:215], v155 offset:39936
	global_load_lds_dwordx4 v128, s[40:41]
	s_mov_b32 m0, s47
	s_nop 0
	global_load_lds_dwordx4 v132, s[40:41]
	s_waitcnt vmcnt(8)
	s_waitcnt lgkmcnt(0)
	s_barrier
	s_setprio 1
	v_mfma_f32_16x16x32_bf16 v[124:127], v[144:147], v[184:187], v[124:127]
	v_mfma_f32_16x16x32_bf16 v[120:123], v[160:163], v[184:187], v[120:123]
	v_mfma_f32_16x16x32_bf16 v[108:111], v[144:147], v[192:195], v[108:111]
	v_mfma_f32_16x16x32_bf16 v[104:107], v[160:163], v[192:195], v[104:107]
	v_mfma_f32_16x16x32_bf16 v[92:95], v[144:147], v[200:203], v[92:95]
	v_mfma_f32_16x16x32_bf16 v[88:91], v[160:163], v[200:203], v[88:91]
	v_mfma_f32_16x16x32_bf16 v[76:79], v[144:147], v[208:211], v[76:79]
	v_mfma_f32_16x16x32_bf16 v[72:75], v[160:163], v[208:211], v[72:75]
	v_mfma_f32_16x16x32_bf16 v[124:127], v[156:159], v[188:191], v[124:127]
	v_mfma_f32_16x16x32_bf16 v[120:123], v[164:167], v[188:191], v[120:123]
	v_mfma_f32_16x16x32_bf16 v[108:111], v[156:159], v[196:199], v[108:111]
	v_mfma_f32_16x16x32_bf16 v[104:107], v[164:167], v[196:199], v[104:107]
	v_mfma_f32_16x16x32_bf16 v[92:95], v[156:159], v[204:207], v[92:95]
	v_mfma_f32_16x16x32_bf16 v[88:91], v[164:167], v[204:207], v[88:91]
	v_mfma_f32_16x16x32_bf16 v[76:79], v[156:159], v[212:215], v[76:79]
	v_mfma_f32_16x16x32_bf16 v[72:75], v[164:167], v[212:215], v[72:75]
	v_mfma_f32_16x16x32_bf16 v[116:119], v[168:171], v[184:187], v[116:119]
	v_mfma_f32_16x16x32_bf16 v[112:115], v[176:179], v[184:187], v[112:115]
	v_mfma_f32_16x16x32_bf16 v[100:103], v[168:171], v[192:195], v[100:103]
	v_mfma_f32_16x16x32_bf16 v[96:99], v[176:179], v[192:195], v[96:99]
	v_mfma_f32_16x16x32_bf16 v[84:87], v[168:171], v[200:203], v[84:87]
	v_mfma_f32_16x16x32_bf16 v[80:83], v[176:179], v[200:203], v[80:83]
	v_mfma_f32_16x16x32_bf16 v[68:71], v[168:171], v[208:211], v[68:71]
	v_mfma_f32_16x16x32_bf16 v[64:67], v[176:179], v[208:211], v[64:67]
	v_mfma_f32_16x16x32_bf16 v[116:119], v[172:175], v[188:191], v[116:119]
	v_mfma_f32_16x16x32_bf16 v[112:115], v[180:183], v[188:191], v[112:115]
	v_mfma_f32_16x16x32_bf16 v[100:103], v[172:175], v[196:199], v[100:103]
	v_mfma_f32_16x16x32_bf16 v[96:99], v[180:183], v[196:199], v[96:99]
	v_mfma_f32_16x16x32_bf16 v[84:87], v[172:175], v[204:207], v[84:87]
	v_mfma_f32_16x16x32_bf16 v[80:83], v[180:183], v[204:207], v[80:83]
	v_mfma_f32_16x16x32_bf16 v[68:71], v[172:175], v[212:215], v[68:71]
	v_mfma_f32_16x16x32_bf16 v[64:67], v[180:183], v[212:215], v[64:67]
	s_setprio 0
	s_barrier
	s_add_i32 s40, s60, s44
	s_add_u32 s80, s38, 0x80
	s_addc_u32 s81, s39, 0
	s_mov_b32 m0, s40
	ds_read_b128 v[184:187], v155 offset:49152
	ds_read_b128 v[188:191], v155 offset:50176
	ds_read_b128 v[192:195], v155 offset:51200
	ds_read_b128 v[196:199], v155 offset:52224
	ds_read_b128 v[200:203], v155 offset:53248
	ds_read_b128 v[204:207], v155 offset:54272
	ds_read_b128 v[208:211], v155 offset:55296
	ds_read_b128 v[212:215], v155 offset:56320
	global_load_lds_dwordx4 v130, s[80:81]
	s_add_i32 m0, s40, 0x2000
	s_add_u32 s38, s38, 0x100080
	s_addc_u32 s39, s39, 0
	s_add_i32 s40, s61, s44
	global_load_lds_dwordx4 v134, s[80:81]
	s_mov_b32 m0, s40
	s_nop 0
	global_load_lds_dwordx4 v130, s[38:39]
	s_add_i32 m0, s40, 0x2000
	s_nop 0
	global_load_lds_dwordx4 v134, s[38:39]
	s_mov_b32 m0, s49
	s_nop 0
	global_load_lds_dwordx4 v128, s[82:83]
	s_mov_b32 m0, s50
	s_nop 0
	global_load_lds_dwordx4 v132, s[82:83]
	s_waitcnt vmcnt(8)
	s_waitcnt lgkmcnt(0)
	s_barrier
	s_setprio 1
	v_mfma_f32_16x16x32_bf16 v[60:63], v[144:147], v[184:187], v[60:63]
	v_mfma_f32_16x16x32_bf16 v[56:59], v[160:163], v[184:187], v[56:59]
	v_mfma_f32_16x16x32_bf16 v[44:47], v[144:147], v[192:195], v[44:47]
	v_mfma_f32_16x16x32_bf16 v[40:43], v[160:163], v[192:195], v[40:43]
	v_mfma_f32_16x16x32_bf16 v[28:31], v[144:147], v[200:203], v[28:31]
	v_mfma_f32_16x16x32_bf16 v[24:27], v[160:163], v[200:203], v[24:27]
	v_mfma_f32_16x16x32_bf16 v[12:15], v[144:147], v[208:211], v[12:15]
	v_mfma_f32_16x16x32_bf16 v[8:11], v[160:163], v[208:211], v[8:11]
	v_mfma_f32_16x16x32_bf16 v[60:63], v[156:159], v[188:191], v[60:63]
	v_mfma_f32_16x16x32_bf16 v[56:59], v[164:167], v[188:191], v[56:59]
	v_mfma_f32_16x16x32_bf16 v[44:47], v[156:159], v[196:199], v[44:47]
	v_mfma_f32_16x16x32_bf16 v[40:43], v[164:167], v[196:199], v[40:43]
	v_mfma_f32_16x16x32_bf16 v[28:31], v[156:159], v[204:207], v[28:31]
	v_mfma_f32_16x16x32_bf16 v[24:27], v[164:167], v[204:207], v[24:27]
	v_mfma_f32_16x16x32_bf16 v[12:15], v[156:159], v[212:215], v[12:15]
	v_mfma_f32_16x16x32_bf16 v[8:11], v[164:167], v[212:215], v[8:11]
	v_mfma_f32_16x16x32_bf16 v[52:55], v[168:171], v[184:187], v[52:55]
	v_mfma_f32_16x16x32_bf16 v[48:51], v[176:179], v[184:187], v[48:51]
	v_mfma_f32_16x16x32_bf16 v[36:39], v[168:171], v[192:195], v[36:39]
	v_mfma_f32_16x16x32_bf16 v[32:35], v[176:179], v[192:195], v[32:35]
	v_mfma_f32_16x16x32_bf16 v[20:23], v[168:171], v[200:203], v[20:23]
	v_mfma_f32_16x16x32_bf16 v[16:19], v[176:179], v[200:203], v[16:19]
	v_mfma_f32_16x16x32_bf16 v[4:7], v[168:171], v[208:211], v[4:7]
	v_mfma_f32_16x16x32_bf16 v[0:3], v[176:179], v[208:211], v[0:3]
	v_mfma_f32_16x16x32_bf16 v[52:55], v[172:175], v[188:191], v[52:55]
	v_mfma_f32_16x16x32_bf16 v[48:51], v[180:183], v[188:191], v[48:51]
	v_mfma_f32_16x16x32_bf16 v[36:39], v[172:175], v[196:199], v[36:39]
	v_mfma_f32_16x16x32_bf16 v[32:35], v[180:183], v[196:199], v[32:35]
	v_mfma_f32_16x16x32_bf16 v[20:23], v[172:175], v[204:207], v[20:23]
	v_mfma_f32_16x16x32_bf16 v[16:19], v[180:183], v[204:207], v[16:19]
	v_mfma_f32_16x16x32_bf16 v[4:7], v[172:175], v[212:215], v[4:7]
	v_mfma_f32_16x16x32_bf16 v[0:3], v[180:183], v[212:215], v[0:3]
	s_setprio 0
	s_add_i32 s59, s59, 2
	s_add_u32 s36, s36, 0x100
	s_addc_u32 s37, s37, 0
	s_add_u32 s57, s57, 0x100
	s_addc_u32 s58, s58, 0
	s_cmp_gt_u32 s59, 61
	s_barrier
	s_cbranch_scc0 .LBB0_2102
	s_and_b64 vcc, exec, s[6:7]
	s_cbranch_vccz .LBB0_2105
	s_barrier
